# MLA q up-projection rope epilogue: per-row scale/cos/sin loads software-pipelined 8 rows ahead through a 9-set VGPR ring (was load->wait per row behind stores), counted vmcnt
# speedup vs baseline: 1.0082x; 1.0040x over previous
; __device__ __forceinline__ uint32_t pk2(float lo, float hi) { typedef float f2 __attribute__((ext_vector_type(2))); const f2 v = {lo, hi}; return __builtin_bit_cast(uint32_t, __builtin_convertvector(v, bf16x2_t)); }
; __device__ __forceinline__ void mla_up_tile(const Params& p, int b, int it, unsigned char* lds) {
;     ...
; #pragma unroll
;         for (int mi = 0; mi < 2; ++mi)
; #pragma unroll
;             for (int reg = 0; reg < 16; ++reg) {
;                 const int m = pm * 128 + wr * 64 + mi * 32 + (reg & 3) + 8 * (reg >> 2) + 4 * h;
;                 const float rq = RQ[m] ;
;                 const float* rp = rope + (size_t)(b * TH + m) * 32;
;                 const float cs = rp[r & 15], sn = rp[16 + (r & 15)];
; #pragma unroll
;                 for (int ni = 0; ni < 4; ++ni) {
;                     const int nb = pn * 256 + wc * 128 + ni * 32, n = nb + r;
;                     float v = acc[mi][ni][reg] * rq;
;                     if (((nb >> 5) % 3) == 2) {
;                         const float o = __builtin_bit_cast(float, __builtin_amdgcn_ds_swizzle(__builtin_bit_cast(int, v), 0x401f));
;                         v = (r < 16) ? (v * cs - o * sn) : (v * cs + o * sn);
;                     }
;                     QF[(size_t)m * 768 + n] = (bf16_t)(pk2(v * qsc, 0.f) & 0xffff);
.LBB0_286:
	s_lshl_b32 s5, s15, 7
	s_waitcnt vmcnt(9)
	v_lshl_add_u32 v132, v188, 6, s5
	v_lshl_or_b32 v134, v186, 2, v132
	v_ashrrev_i32_e32 v135, 31, v134
	v_lshl_add_u64 v[132:133], v[134:135], 2, s[28:29]
	v_and_b32_e32 v130, 15, v187
	v_mov_b32_e32 v224, v132
	v_mov_b32_e32 v225, v133
	v_add_u32_e32 v132, s13, v134
	v_lshlrev_b32_e32 v130, 2, v130
	v_mov_b32_e32 v131, v1
	v_ashrrev_i32_e32 v133, 31, v132
	v_lshl_add_u64 v[130:131], s[30:31], 0, v[130:131]
	v_lshlrev_b64 v[132:133], 7, v[132:133]
	v_lshl_add_u64 v[132:133], v[130:131], 0, v[132:133]
	v_mov_b32_e32 v226, v132
	v_mov_b32_e32 v227, v133
	v_add_co_u32_e32 v234, vcc, 0x1000, v132
	v_addc_co_u32_e32 v235, vcc, 0, v133, vcc
	global_load_dword v192, v[224:225], off
	global_load_dword v193, v[226:227], off
	global_load_dword v194, v[226:227], off offset:64
	global_load_dword v195, v[224:225], off offset:4
	global_load_dword v196, v[226:227], off offset:128
	global_load_dword v197, v[226:227], off offset:192
	global_load_dword v198, v[224:225], off offset:8
	global_load_dword v199, v[226:227], off offset:256
	global_load_dword v200, v[226:227], off offset:320
	global_load_dword v201, v[224:225], off offset:12
	global_load_dword v202, v[226:227], off offset:384
	global_load_dword v203, v[226:227], off offset:448
	global_load_dword v204, v[224:225], off offset:32
	global_load_dword v205, v[226:227], off offset:1024
	global_load_dword v206, v[226:227], off offset:1088
	global_load_dword v207, v[224:225], off offset:36
	global_load_dword v208, v[226:227], off offset:1152
	global_load_dword v209, v[226:227], off offset:1216
	global_load_dword v210, v[224:225], off offset:40
	global_load_dword v211, v[226:227], off offset:1280
	global_load_dword v212, v[226:227], off offset:1344
	global_load_dword v213, v[224:225], off offset:44
	global_load_dword v214, v[226:227], off offset:1408
	global_load_dword v215, v[226:227], off offset:1472
	global_load_dword v216, v[224:225], off offset:64
	global_load_dword v217, v[226:227], off offset:2048
	global_load_dword v218, v[226:227], off offset:2112
	s_lshl_b32 s4, s4, 8
	v_lshl_or_b32 v136, v181, 7, s4
	s_waitcnt vmcnt(34)
	v_ashrrev_i32_e32 v142, 5, v136
	s_mov_b32 s4, 0x55555556
	v_mul_hi_i32 v132, v142, s4
	v_lshrrev_b32_e32 v133, 31, v132
	v_add_u32_e32 v132, v132, v133
	v_lshl_add_u32 v132, v132, 1, v132
	v_sub_u32_e32 v132, v142, v132
	v_cmp_gt_u32_e32 vcc, 16, v0
	v_cmp_eq_u32_e64 s[40:41], 2, v132
	s_waitcnt vmcnt(24)
	v_mul_f32_e32 v114, v114, v192
	s_and_saveexec_b64 s[4:5], s[40:41]
	s_cbranch_execz .LBB0_288
	ds_swizzle_b32 v132, v114 offset:swizzle(SWAP,16)
	s_waitcnt lgkmcnt(0)
	v_mul_f32_e32 v132, v194, v132
	v_cndmask_b32_e64 v132, v132, -v132, vcc
	v_fmac_f32_e32 v132, v193, v114
	v_mov_b32_e32 v114, v132
.LBB0_288:
	s_or_b64 exec, exec, s[4:5]
	v_mov_b64_e32 v[132:133], s[34:35]
	v_mad_i64_i32 v[138:139], s[4:5], v134, s65, v[132:133]
	v_or_b32_e32 v132, v136, v0
	v_mul_f32_e32 v114, 0x3e16c740, v114
	v_ashrrev_i32_e32 v133, 31, v132
	v_cvt_pk_bf16_f32 v114, v114, s0
	v_lshl_add_u64 v[144:145], v[132:133], 1, v[138:139]
	global_store_short v[144:145], v114, off
	v_or_b32_e32 v114, 1, v142
	s_mov_b32 s4, 0x55555556
	v_mul_hi_i32 v137, v114, s4
	v_lshrrev_b32_e32 v143, 31, v137
	v_add_u32_e32 v137, v137, v143
	v_lshl_add_u32 v137, v137, 1, v137
	v_sub_u32_e32 v114, v114, v137
	v_mul_f32_e32 v98, v98, v192
	v_cmp_eq_u32_e64 s[42:43], 2, v114
	s_and_saveexec_b64 s[4:5], s[42:43]
	s_cbranch_execz .LBB0_290
	ds_swizzle_b32 v114, v98 offset:swizzle(SWAP,16)
	s_waitcnt lgkmcnt(0)
	v_mul_f32_e32 v114, v194, v114
	v_cndmask_b32_e64 v114, v114, -v114, vcc
	v_fmac_f32_e32 v114, v193, v98
	v_mov_b32_e32 v98, v114
.LBB0_290:
	s_or_b64 exec, exec, s[4:5]
	v_ashrrev_i32_e32 v137, 31, v136
	v_mul_f32_e32 v98, 0x3e16c740, v98
	v_lshl_add_u64 v[136:137], v[136:137], 0, v[0:1]
	v_cvt_pk_bf16_f32 v98, v98, s0
	v_lshl_add_u64 v[138:139], v[136:137], 1, v[138:139]
	v_mul_f32_e32 v0, v82, v192
	v_or_b32_e32 v82, 2, v142
	s_mov_b32 s4, 0x55555556
	global_store_short v[138:139], v98, off offset:64
	v_mul_hi_i32 v98, v82, s4
	v_lshrrev_b32_e32 v114, 31, v98
	v_add_u32_e32 v98, v98, v114
	v_lshl_add_u32 v98, v98, 1, v98
	v_sub_u32_e32 v82, v82, v98
	v_cmp_eq_u32_e64 s[44:45], 2, v82
	s_and_saveexec_b64 s[4:5], s[44:45]
	s_cbranch_execz .LBB0_292
	ds_swizzle_b32 v82, v0 offset:swizzle(SWAP,16)
	s_waitcnt lgkmcnt(0)
	v_mul_f32_e32 v82, v194, v82
	v_cndmask_b32_e64 v82, v82, -v82, vcc
	v_fmac_f32_e32 v82, v193, v0
	v_mov_b32_e32 v0, v82
.LBB0_292:
	s_or_b64 exec, exec, s[4:5]
	v_mul_f32_e32 v0, 0x3e16c740, v0
	v_cvt_pk_bf16_f32 v0, v0, s0
	global_store_short v[138:139], v0, off offset:128
	v_mul_f32_e32 v0, v66, v192
	v_or_b32_e32 v66, 3, v142
	s_mov_b32 s4, 0x55555556
	v_mul_hi_i32 v82, v66, s4
	v_lshrrev_b32_e32 v98, 31, v82
	v_add_u32_e32 v82, v82, v98
	v_lshl_add_u32 v82, v82, 1, v82
	v_sub_u32_e32 v66, v66, v82
	v_cmp_eq_u32_e64 s[46:47], 2, v66
	s_and_saveexec_b64 s[4:5], s[46:47]
	s_cbranch_execz .LBB0_294
	ds_swizzle_b32 v66, v0 offset:swizzle(SWAP,16)
	s_waitcnt lgkmcnt(0)
	v_mul_f32_e32 v66, v194, v66
	v_cndmask_b32_e64 v66, v66, -v66, vcc
	v_fmac_f32_e32 v66, v193, v0
	v_mov_b32_e32 v0, v66
.LBB0_294:
	s_or_b64 exec, exec, s[4:5]
	v_mul_f32_e32 v0, 0x3e16c740, v0
	v_cvt_pk_bf16_f32 v0, v0, s0
	global_store_short v[138:139], v0, off offset:192
	v_or_b32_e32 v138, 1, v134
	v_ashrrev_i32_e32 v139, 31, v138
	v_lshl_add_u64 v[140:141], v[138:139], 2, s[28:29]
	global_load_dword v192, v[224:225], off offset:68
	global_load_dword v193, v[226:227], off offset:2176
	global_load_dword v194, v[226:227], off offset:2240
	v_add_u32_e32 v140, s13, v138
	v_ashrrev_i32_e32 v141, 31, v140
	v_lshlrev_b64 v[140:141], 7, v[140:141]
	v_lshl_add_u64 v[140:141], v[130:131], 0, v[140:141]
	s_waitcnt vmcnt(28)
	v_mul_f32_e32 v98, v115, v195
	s_and_saveexec_b64 s[4:5], s[40:41]
	s_cbranch_execz .LBB0_296
	ds_swizzle_b32 v114, v98 offset:swizzle(SWAP,16)
	s_waitcnt lgkmcnt(0)
	v_mul_f32_e32 v114, v197, v114
	v_cndmask_b32_e64 v114, v114, -v114, vcc
	v_fmac_f32_e32 v114, v196, v98
	v_mov_b32_e32 v98, v114
; __device__ __forceinline__ uint32_t pk2(float lo, float hi) { typedef float f2 __attribute__((ext_vector_type(2))); const f2 v = {lo, hi}; return __builtin_bit_cast(uint32_t, __builtin_convertvector(v, bf16x2_t)); }
; __device__ __forceinline__ void mla_up_tile(const Params& p, int b, int it, unsigned char* lds) {
;     ...
; #pragma unroll
;         for (int mi = 0; mi < 2; ++mi)
; #pragma unroll
;             for (int reg = 0; reg < 16; ++reg) {
;                 const int m = pm * 128 + wr * 64 + mi * 32 + (reg & 3) + 8 * (reg >> 2) + 4 * h;
;                 const float rq = RQ[m] ;
;                 const float* rp = rope + (size_t)(b * TH + m) * 32;
;                 const float cs = rp[r & 15], sn = rp[16 + (r & 15)];
; #pragma unroll
;                 for (int ni = 0; ni < 4; ++ni) {
;                     const int nb = pn * 256 + wc * 128 + ni * 32, n = nb + r;
;                     float v = acc[mi][ni][reg] * rq;
;                     if (((nb >> 5) % 3) == 2) {
;                         const float o = __builtin_bit_cast(float, __builtin_amdgcn_ds_swizzle(__builtin_bit_cast(int, v), 0x401f));
;                         v = (r < 16) ? (v * cs - o * sn) : (v * cs + o * sn);
;                     }
;                     QF[(size_t)m * 768 + n] = (bf16_t)(pk2(v * qsc, 0.f) & 0xffff);
.LBB0_296:
	s_or_b64 exec, exec, s[4:5]
	v_mov_b64_e32 v[114:115], s[34:35]
	v_mad_i64_i32 v[114:115], s[4:5], v138, s65, v[114:115]
	v_mul_f32_e32 v98, 0x3e16c740, v98
	v_cvt_pk_bf16_f32 v98, v98, s0
	v_lshl_add_u64 v[138:139], v[132:133], 1, v[114:115]
	global_store_short v[138:139], v98, off
	v_mul_f32_e32 v98, v99, v195
	s_and_saveexec_b64 s[4:5], s[42:43]
	s_cbranch_execz .LBB0_298
	ds_swizzle_b32 v99, v98 offset:swizzle(SWAP,16)
	s_waitcnt lgkmcnt(0)
	v_mul_f32_e32 v99, v197, v99
	v_cndmask_b32_e64 v99, v99, -v99, vcc
	v_fmac_f32_e32 v99, v196, v98
	v_mov_b32_e32 v98, v99
.LBB0_298:
	s_or_b64 exec, exec, s[4:5]
	v_mul_f32_e32 v98, 0x3e16c740, v98
	v_cvt_pk_bf16_f32 v135, v98, s0
	v_lshl_add_u64 v[98:99], v[136:137], 1, v[114:115]
	v_mul_f32_e32 v83, v83, v195
	global_store_short v[98:99], v135, off offset:64
	s_and_saveexec_b64 s[4:5], s[44:45]
	s_cbranch_execz .LBB0_300
	ds_swizzle_b32 v114, v83 offset:swizzle(SWAP,16)
	s_waitcnt lgkmcnt(0)
	v_mul_f32_e32 v114, v197, v114
	v_cndmask_b32_e64 v114, v114, -v114, vcc
	v_fmac_f32_e32 v114, v196, v83
	v_mov_b32_e32 v83, v114
.LBB0_300:
	s_or_b64 exec, exec, s[4:5]
	v_mul_f32_e32 v83, 0x3e16c740, v83
	v_cvt_pk_bf16_f32 v83, v83, s0
	v_mul_f32_e32 v0, v67, v195
	global_store_short v[98:99], v83, off offset:128
	s_and_saveexec_b64 s[4:5], s[46:47]
	s_cbranch_execz .LBB0_302
	ds_swizzle_b32 v67, v0 offset:swizzle(SWAP,16)
	s_waitcnt lgkmcnt(0)
	v_mul_f32_e32 v67, v197, v67
	v_cndmask_b32_e64 v67, v67, -v67, vcc
	v_fmac_f32_e32 v67, v196, v0
	v_mov_b32_e32 v0, v67
.LBB0_302:
	s_or_b64 exec, exec, s[4:5]
	v_or_b32_e32 v66, 2, v134
	v_mul_f32_e32 v0, 0x3e16c740, v0
	v_ashrrev_i32_e32 v67, 31, v66
	v_cvt_pk_bf16_f32 v0, v0, s0
	v_lshl_add_u64 v[82:83], v[66:67], 2, s[28:29]
	global_store_short v[98:99], v0, off offset:192
	global_load_dword v195, v[224:225], off offset:72
	global_load_dword v196, v[226:227], off offset:2304
	global_load_dword v197, v[226:227], off offset:2368
	v_add_u32_e32 v82, s13, v66
	v_ashrrev_i32_e32 v83, 31, v82
	v_lshlrev_b64 v[82:83], 7, v[82:83]
	v_lshl_add_u64 v[98:99], v[130:131], 0, v[82:83]
	s_waitcnt vmcnt(32)
	v_mul_f32_e32 v98, v116, v198
	s_and_saveexec_b64 s[4:5], s[40:41]
	s_cbranch_execz .LBB0_304
	ds_swizzle_b32 v67, v98 offset:swizzle(SWAP,16)
	s_waitcnt lgkmcnt(0)
	v_mul_f32_e32 v67, v200, v67
	v_cndmask_b32_e64 v67, v67, -v67, vcc
	v_fmac_f32_e32 v67, v199, v98
	v_mov_b32_e32 v98, v67
.LBB0_304:
	s_or_b64 exec, exec, s[4:5]
	v_mov_b64_e32 v[114:115], s[34:35]
	v_mad_i64_i32 v[66:67], s[4:5], v66, s65, v[114:115]
	v_mul_f32_e32 v98, 0x3e16c740, v98
	v_cvt_pk_bf16_f32 v114, v98, s0
	v_lshl_add_u64 v[98:99], v[132:133], 1, v[66:67]
	global_store_short v[98:99], v114, off
	v_mul_f32_e32 v98, v100, v198
	s_and_saveexec_b64 s[4:5], s[42:43]
	s_cbranch_execz .LBB0_306
	ds_swizzle_b32 v99, v98 offset:swizzle(SWAP,16)
	s_waitcnt lgkmcnt(0)
	v_mul_f32_e32 v99, v200, v99
	v_cndmask_b32_e64 v99, v99, -v99, vcc
	v_fmac_f32_e32 v99, v199, v98
	v_mov_b32_e32 v98, v99
.LBB0_306:
	s_or_b64 exec, exec, s[4:5]
	v_mul_f32_e32 v98, 0x3e16c740, v98
	v_cvt_pk_bf16_f32 v98, v98, s0
	v_lshl_add_u64 v[66:67], v[136:137], 1, v[66:67]
	v_mul_f32_e32 v84, v84, v198
	global_store_short v[66:67], v98, off offset:64
	s_and_saveexec_b64 s[4:5], s[44:45]
	s_cbranch_execz .LBB0_308
	ds_swizzle_b32 v98, v84 offset:swizzle(SWAP,16)
	s_waitcnt lgkmcnt(0)
	v_mul_f32_e32 v98, v200, v98
	v_cndmask_b32_e64 v98, v98, -v98, vcc
	v_fmac_f32_e32 v98, v199, v84
	v_mov_b32_e32 v84, v98
.LBB0_308:
	s_or_b64 exec, exec, s[4:5]
	v_mul_f32_e32 v84, 0x3e16c740, v84
	v_cvt_pk_bf16_f32 v84, v84, s0
	v_mul_f32_e32 v0, v68, v198
	global_store_short v[66:67], v84, off offset:128
	s_and_saveexec_b64 s[4:5], s[46:47]
	s_cbranch_execz .LBB0_310
	ds_swizzle_b32 v68, v0 offset:swizzle(SWAP,16)
	s_waitcnt lgkmcnt(0)
	v_mul_f32_e32 v68, v200, v68
	v_cndmask_b32_e64 v68, v68, -v68, vcc
	v_fmac_f32_e32 v68, v199, v0
	v_mov_b32_e32 v0, v68
.LBB0_310:
	s_or_b64 exec, exec, s[4:5]
	v_mul_f32_e32 v0, 0x3e16c740, v0
	v_cvt_pk_bf16_f32 v0, v0, s0
	global_store_short v[66:67], v0, off offset:192
	v_or_b32_e32 v66, 3, v134
	v_ashrrev_i32_e32 v67, 31, v66
	v_lshl_add_u64 v[82:83], v[66:67], 2, s[28:29]
	global_load_dword v198, v[224:225], off offset:76
	global_load_dword v199, v[226:227], off offset:2432
	global_load_dword v200, v[226:227], off offset:2496
	v_add_u32_e32 v82, s13, v66
	v_ashrrev_i32_e32 v83, 31, v82
	v_lshlrev_b64 v[82:83], 7, v[82:83]
	v_lshl_add_u64 v[82:83], v[130:131], 0, v[82:83]
	s_nop 0
	s_waitcnt vmcnt(36)
	v_mul_f32_e32 v83, v117, v201
	s_and_saveexec_b64 s[4:5], s[40:41]
	s_cbranch_execz .LBB0_312
	ds_swizzle_b32 v67, v83 offset:swizzle(SWAP,16)
	s_waitcnt lgkmcnt(0)
	v_mul_f32_e32 v67, v203, v67
	v_cndmask_b32_e64 v67, v67, -v67, vcc
	v_fmac_f32_e32 v67, v202, v83
	v_mov_b32_e32 v83, v67
.LBB0_312:
	s_or_b64 exec, exec, s[4:5]
	v_mov_b64_e32 v[98:99], s[34:35]
	v_mad_i64_i32 v[66:67], s[4:5], v66, s65, v[98:99]
	v_mul_f32_e32 v83, 0x3e16c740, v83
	v_cvt_pk_bf16_f32 v83, v83, s0
	v_lshl_add_u64 v[98:99], v[132:133], 1, v[66:67]
	global_store_short v[98:99], v83, off
	v_mul_f32_e32 v83, v101, v201
	s_and_saveexec_b64 s[4:5], s[42:43]
	s_cbranch_execz .LBB0_314
	ds_swizzle_b32 v84, v83 offset:swizzle(SWAP,16)
	s_waitcnt lgkmcnt(0)
	v_mul_f32_e32 v84, v203, v84
	v_cndmask_b32_e64 v84, v84, -v84, vcc
	v_fmac_f32_e32 v84, v202, v83
	v_mov_b32_e32 v83, v84
.LBB0_314:
	s_or_b64 exec, exec, s[4:5]
	v_mul_f32_e32 v83, 0x3e16c740, v83
	v_cvt_pk_bf16_f32 v83, v83, s0
	v_lshl_add_u64 v[66:67], v[136:137], 1, v[66:67]
	global_store_short v[66:67], v83, off offset:64
	v_mul_f32_e32 v83, v85, v201
	s_and_saveexec_b64 s[4:5], s[44:45]
	s_cbranch_execz .LBB0_316
	ds_swizzle_b32 v84, v83 offset:swizzle(SWAP,16)
	s_waitcnt lgkmcnt(0)
	v_mul_f32_e32 v84, v203, v84
	v_cndmask_b32_e64 v84, v84, -v84, vcc
	v_fmac_f32_e32 v84, v202, v83
	v_mov_b32_e32 v83, v84
; __device__ __forceinline__ uint32_t pk2(float lo, float hi) { typedef float f2 __attribute__((ext_vector_type(2))); const f2 v = {lo, hi}; return __builtin_bit_cast(uint32_t, __builtin_convertvector(v, bf16x2_t)); }
; __device__ __forceinline__ void mla_up_tile(const Params& p, int b, int it, unsigned char* lds) {
;     ...
; #pragma unroll
;         for (int mi = 0; mi < 2; ++mi)
; #pragma unroll
;             for (int reg = 0; reg < 16; ++reg) {
;                 const int m = pm * 128 + wr * 64 + mi * 32 + (reg & 3) + 8 * (reg >> 2) + 4 * h;
;                 const float rq = RQ[m] ;
;                 const float* rp = rope + (size_t)(b * TH + m) * 32;
;                 const float cs = rp[r & 15], sn = rp[16 + (r & 15)];
; #pragma unroll
;                 for (int ni = 0; ni < 4; ++ni) {
;                     const int nb = pn * 256 + wc * 128 + ni * 32, n = nb + r;
;                     float v = acc[mi][ni][reg] * rq;
;                     if (((nb >> 5) % 3) == 2) {
;                         const float o = __builtin_bit_cast(float, __builtin_amdgcn_ds_swizzle(__builtin_bit_cast(int, v), 0x401f));
;                         v = (r < 16) ? (v * cs - o * sn) : (v * cs + o * sn);
;                     }
;                     QF[(size_t)m * 768 + n] = (bf16_t)(pk2(v * qsc, 0.f) & 0xffff);
.LBB0_316:
	s_or_b64 exec, exec, s[4:5]
	v_mul_f32_e32 v83, 0x3e16c740, v83
	v_cvt_pk_bf16_f32 v83, v83, s0
	v_mul_f32_e32 v0, v69, v201
	global_store_short v[66:67], v83, off offset:128
	s_and_saveexec_b64 s[4:5], s[46:47]
	s_cbranch_execz .LBB0_318
	ds_swizzle_b32 v69, v0 offset:swizzle(SWAP,16)
	s_waitcnt lgkmcnt(0)
	v_mul_f32_e32 v69, v203, v69
	v_cndmask_b32_e64 v69, v69, -v69, vcc
	v_fmac_f32_e32 v69, v202, v0
	v_mov_b32_e32 v0, v69
.LBB0_318:
	s_or_b64 exec, exec, s[4:5]
	v_mul_f32_e32 v0, 0x3e16c740, v0
	v_cvt_pk_bf16_f32 v0, v0, s0
	global_store_short v[66:67], v0, off offset:192
	v_or_b32_e32 v66, 8, v134
	v_ashrrev_i32_e32 v67, 31, v66
	v_lshl_add_u64 v[68:69], v[66:67], 2, s[28:29]
	global_load_dword v201, v[224:225], off offset:96
	global_load_dword v202, v[226:227], off offset:3072
	global_load_dword v203, v[226:227], off offset:3136
	v_add_u32_e32 v68, s13, v66
	v_ashrrev_i32_e32 v69, 31, v68
	v_lshlrev_b64 v[68:69], 7, v[68:69]
	v_lshl_add_u64 v[82:83], v[130:131], 0, v[68:69]
	s_waitcnt vmcnt(40)
	v_mul_f32_e32 v82, v118, v204
	s_and_saveexec_b64 s[4:5], s[40:41]
	s_cbranch_execz .LBB0_320
	ds_swizzle_b32 v67, v82 offset:swizzle(SWAP,16)
	s_waitcnt lgkmcnt(0)
	v_mul_f32_e32 v67, v206, v67
	v_cndmask_b32_e64 v67, v67, -v67, vcc
	v_fmac_f32_e32 v67, v205, v82
	v_mov_b32_e32 v82, v67
.LBB0_320:
	s_or_b64 exec, exec, s[4:5]
	v_mov_b64_e32 v[84:85], s[34:35]
	v_mad_i64_i32 v[66:67], s[4:5], v66, s65, v[84:85]
	v_mul_f32_e32 v82, 0x3e16c740, v82
	v_cvt_pk_bf16_f32 v84, v82, s0
	v_lshl_add_u64 v[82:83], v[132:133], 1, v[66:67]
	global_store_short v[82:83], v84, off
	v_mul_f32_e32 v82, v102, v204
	s_and_saveexec_b64 s[4:5], s[42:43]
	s_cbranch_execz .LBB0_322
	ds_swizzle_b32 v83, v82 offset:swizzle(SWAP,16)
	s_waitcnt lgkmcnt(0)
	v_mul_f32_e32 v83, v206, v83
	v_cndmask_b32_e64 v83, v83, -v83, vcc
	v_fmac_f32_e32 v83, v205, v82
	v_mov_b32_e32 v82, v83
.LBB0_322:
	s_or_b64 exec, exec, s[4:5]
	v_mul_f32_e32 v82, 0x3e16c740, v82
	v_cvt_pk_bf16_f32 v82, v82, s0
	v_lshl_add_u64 v[66:67], v[136:137], 1, v[66:67]
	global_store_short v[66:67], v82, off offset:64
	v_mul_f32_e32 v82, v86, v204
	s_and_saveexec_b64 s[4:5], s[44:45]
	s_cbranch_execz .LBB0_324
	ds_swizzle_b32 v83, v82 offset:swizzle(SWAP,16)
	s_waitcnt lgkmcnt(0)
	v_mul_f32_e32 v83, v206, v83
	v_cndmask_b32_e64 v83, v83, -v83, vcc
	v_fmac_f32_e32 v83, v205, v82
	v_mov_b32_e32 v82, v83
.LBB0_324:
	s_or_b64 exec, exec, s[4:5]
	v_mul_f32_e32 v82, 0x3e16c740, v82
	v_cvt_pk_bf16_f32 v82, v82, s0
	v_mul_f32_e32 v0, v70, v204
	global_store_short v[66:67], v82, off offset:128
	s_and_saveexec_b64 s[4:5], s[46:47]
	s_cbranch_execz .LBB0_326
	ds_swizzle_b32 v70, v0 offset:swizzle(SWAP,16)
	s_waitcnt lgkmcnt(0)
	v_mul_f32_e32 v69, v206, v70
	v_cndmask_b32_e64 v69, v69, -v69, vcc
	v_fmac_f32_e32 v69, v205, v0
	v_mov_b32_e32 v0, v69
.LBB0_326:
	s_or_b64 exec, exec, s[4:5]
	v_mul_f32_e32 v0, 0x3e16c740, v0
	v_cvt_pk_bf16_f32 v0, v0, s0
	global_store_short v[66:67], v0, off offset:192
	v_or_b32_e32 v66, 9, v134
	v_ashrrev_i32_e32 v67, 31, v66
	v_lshl_add_u64 v[68:69], v[66:67], 2, s[28:29]
	global_load_dword v204, v[224:225], off offset:100
	global_load_dword v205, v[226:227], off offset:3200
	global_load_dword v206, v[226:227], off offset:3264
	v_add_u32_e32 v68, s13, v66
	v_ashrrev_i32_e32 v69, 31, v68
	v_lshlrev_b64 v[68:69], 7, v[68:69]
	v_lshl_add_u64 v[82:83], v[130:131], 0, v[68:69]
	s_waitcnt vmcnt(44)
	v_mul_f32_e32 v70, v119, v207
	s_and_saveexec_b64 s[4:5], s[40:41]
	s_cbranch_execz .LBB0_328
	ds_swizzle_b32 v67, v70 offset:swizzle(SWAP,16)
	s_waitcnt lgkmcnt(0)
	v_mul_f32_e32 v67, v209, v67
	v_cndmask_b32_e64 v67, v67, -v67, vcc
	v_fmac_f32_e32 v67, v208, v70
	v_mov_b32_e32 v70, v67
.LBB0_328:
	s_or_b64 exec, exec, s[4:5]
	v_mov_b64_e32 v[82:83], s[34:35]
	v_mad_i64_i32 v[66:67], s[4:5], v66, s65, v[82:83]
	v_mul_f32_e32 v70, 0x3e16c740, v70
	v_cvt_pk_bf16_f32 v70, v70, s0
	v_lshl_add_u64 v[82:83], v[132:133], 1, v[66:67]
	global_store_short v[82:83], v70, off
	v_mul_f32_e32 v70, v103, v207
	s_and_saveexec_b64 s[4:5], s[42:43]
	s_cbranch_execz .LBB0_330
	ds_swizzle_b32 v82, v70 offset:swizzle(SWAP,16)
	s_waitcnt lgkmcnt(0)
	v_mul_f32_e32 v82, v209, v82
	v_cndmask_b32_e64 v82, v82, -v82, vcc
	v_fmac_f32_e32 v82, v208, v70
	v_mov_b32_e32 v70, v82
.LBB0_330:
	s_or_b64 exec, exec, s[4:5]
	v_mul_f32_e32 v70, 0x3e16c740, v70
	v_cvt_pk_bf16_f32 v70, v70, s0
	v_lshl_add_u64 v[66:67], v[136:137], 1, v[66:67]
	global_store_short v[66:67], v70, off offset:64
	v_mul_f32_e32 v70, v87, v207
	s_and_saveexec_b64 s[4:5], s[44:45]
	s_cbranch_execz .LBB0_332
	ds_swizzle_b32 v82, v70 offset:swizzle(SWAP,16)
	s_waitcnt lgkmcnt(0)
	v_mul_f32_e32 v82, v209, v82
	v_cndmask_b32_e64 v82, v82, -v82, vcc
	v_fmac_f32_e32 v82, v208, v70
	v_mov_b32_e32 v70, v82
.LBB0_332:
	s_or_b64 exec, exec, s[4:5]
	v_mul_f32_e32 v70, 0x3e16c740, v70
	v_cvt_pk_bf16_f32 v70, v70, s0
	v_mul_f32_e32 v0, v71, v207
	global_store_short v[66:67], v70, off offset:128
	s_and_saveexec_b64 s[4:5], s[46:47]
	s_cbranch_execz .LBB0_334
	ds_swizzle_b32 v70, v0 offset:swizzle(SWAP,16)
	s_waitcnt lgkmcnt(0)
	v_mul_f32_e32 v69, v209, v70
	v_cndmask_b32_e64 v69, v69, -v69, vcc
	v_fmac_f32_e32 v69, v208, v0
	v_mov_b32_e32 v0, v69
; __device__ __forceinline__ uint32_t pk2(float lo, float hi) { typedef float f2 __attribute__((ext_vector_type(2))); const f2 v = {lo, hi}; return __builtin_bit_cast(uint32_t, __builtin_convertvector(v, bf16x2_t)); }
; __device__ __forceinline__ void mla_up_tile(const Params& p, int b, int it, unsigned char* lds) {
;     ...
; #pragma unroll
;         for (int mi = 0; mi < 2; ++mi)
; #pragma unroll
;             for (int reg = 0; reg < 16; ++reg) {
;                 const int m = pm * 128 + wr * 64 + mi * 32 + (reg & 3) + 8 * (reg >> 2) + 4 * h;
;                 const float rq = RQ[m] ;
;                 const float* rp = rope + (size_t)(b * TH + m) * 32;
;                 const float cs = rp[r & 15], sn = rp[16 + (r & 15)];
; #pragma unroll
;                 for (int ni = 0; ni < 4; ++ni) {
;                     const int nb = pn * 256 + wc * 128 + ni * 32, n = nb + r;
;                     float v = acc[mi][ni][reg] * rq;
;                     if (((nb >> 5) % 3) == 2) {
;                         const float o = __builtin_bit_cast(float, __builtin_amdgcn_ds_swizzle(__builtin_bit_cast(int, v), 0x401f));
;                         v = (r < 16) ? (v * cs - o * sn) : (v * cs + o * sn);
;                     }
;                     QF[(size_t)m * 768 + n] = (bf16_t)(pk2(v * qsc, 0.f) & 0xffff);
.LBB0_334:
	s_or_b64 exec, exec, s[4:5]
	v_mul_f32_e32 v0, 0x3e16c740, v0
	v_cvt_pk_bf16_f32 v0, v0, s0
	global_store_short v[66:67], v0, off offset:192
	v_or_b32_e32 v66, 10, v134
	v_ashrrev_i32_e32 v67, 31, v66
	v_lshl_add_u64 v[68:69], v[66:67], 2, s[28:29]
	global_load_dword v207, v[224:225], off offset:104
	global_load_dword v208, v[226:227], off offset:3328
	global_load_dword v209, v[226:227], off offset:3392
	v_add_u32_e32 v68, s13, v66
	v_ashrrev_i32_e32 v69, 31, v68
	v_lshlrev_b64 v[68:69], 7, v[68:69]
	v_lshl_add_u64 v[70:71], v[130:131], 0, v[68:69]
	s_waitcnt vmcnt(48)
	v_mul_f32_e32 v70, v120, v210
	s_and_saveexec_b64 s[4:5], s[40:41]
	s_cbranch_execz .LBB0_336
	ds_swizzle_b32 v67, v70 offset:swizzle(SWAP,16)
	s_waitcnt lgkmcnt(0)
	v_mul_f32_e32 v67, v212, v67
	v_cndmask_b32_e64 v67, v67, -v67, vcc
	v_fmac_f32_e32 v67, v211, v70
	v_mov_b32_e32 v70, v67
.LBB0_336:
	s_or_b64 exec, exec, s[4:5]
	v_mov_b64_e32 v[82:83], s[34:35]
	v_mad_i64_i32 v[66:67], s[4:5], v66, s65, v[82:83]
	v_mul_f32_e32 v70, 0x3e16c740, v70
	v_cvt_pk_bf16_f32 v82, v70, s0
	v_lshl_add_u64 v[70:71], v[132:133], 1, v[66:67]
	global_store_short v[70:71], v82, off
	v_mul_f32_e32 v70, v104, v210
	s_and_saveexec_b64 s[4:5], s[42:43]
	s_cbranch_execz .LBB0_338
	ds_swizzle_b32 v71, v70 offset:swizzle(SWAP,16)
	s_waitcnt lgkmcnt(0)
	v_mul_f32_e32 v71, v212, v71
	v_cndmask_b32_e64 v71, v71, -v71, vcc
	v_fmac_f32_e32 v71, v211, v70
	v_mov_b32_e32 v70, v71
.LBB0_338:
	s_or_b64 exec, exec, s[4:5]
	v_mul_f32_e32 v70, 0x3e16c740, v70
	v_cvt_pk_bf16_f32 v70, v70, s0
	v_lshl_add_u64 v[66:67], v[136:137], 1, v[66:67]
	global_store_short v[66:67], v70, off offset:64
	v_mul_f32_e32 v70, v88, v210
	s_and_saveexec_b64 s[4:5], s[44:45]
	s_cbranch_execz .LBB0_340
	ds_swizzle_b32 v71, v70 offset:swizzle(SWAP,16)
	s_waitcnt lgkmcnt(0)
	v_mul_f32_e32 v71, v212, v71
	v_cndmask_b32_e64 v71, v71, -v71, vcc
	v_fmac_f32_e32 v71, v211, v70
	v_mov_b32_e32 v70, v71
.LBB0_340:
	s_or_b64 exec, exec, s[4:5]
	v_mul_f32_e32 v70, 0x3e16c740, v70
	v_cvt_pk_bf16_f32 v70, v70, s0
	v_mul_f32_e32 v0, v72, v210
	global_store_short v[66:67], v70, off offset:128
	s_and_saveexec_b64 s[4:5], s[46:47]
	s_cbranch_execz .LBB0_342
	ds_swizzle_b32 v70, v0 offset:swizzle(SWAP,16)
	s_waitcnt lgkmcnt(0)
	v_mul_f32_e32 v69, v212, v70
	v_cndmask_b32_e64 v69, v69, -v69, vcc
	v_fmac_f32_e32 v69, v211, v0
	v_mov_b32_e32 v0, v69
.LBB0_342:
	s_or_b64 exec, exec, s[4:5]
	v_mul_f32_e32 v0, 0x3e16c740, v0
	v_cvt_pk_bf16_f32 v0, v0, s0
	global_store_short v[66:67], v0, off offset:192
	v_or_b32_e32 v66, 11, v134
	v_ashrrev_i32_e32 v67, 31, v66
	v_lshl_add_u64 v[68:69], v[66:67], 2, s[28:29]
	global_load_dword v210, v[224:225], off offset:108
	global_load_dword v211, v[226:227], off offset:3456
	global_load_dword v212, v[226:227], off offset:3520
	v_add_u32_e32 v68, s13, v66
	v_ashrrev_i32_e32 v69, 31, v68
	v_lshlrev_b64 v[68:69], 7, v[68:69]
	v_lshl_add_u64 v[70:71], v[130:131], 0, v[68:69]
	s_waitcnt vmcnt(52)
	v_mul_f32_e32 v70, v121, v213
	s_and_saveexec_b64 s[4:5], s[40:41]
	s_cbranch_execz .LBB0_344
	ds_swizzle_b32 v67, v70 offset:swizzle(SWAP,16)
	s_waitcnt lgkmcnt(0)
	v_mul_f32_e32 v67, v215, v67
	v_cndmask_b32_e64 v67, v67, -v67, vcc
	v_fmac_f32_e32 v67, v214, v70
	v_mov_b32_e32 v70, v67
.LBB0_344:
	s_or_b64 exec, exec, s[4:5]
	v_mov_b64_e32 v[82:83], s[34:35]
	v_mad_i64_i32 v[66:67], s[4:5], v66, s65, v[82:83]
	v_mul_f32_e32 v70, 0x3e16c740, v70
	v_cvt_pk_bf16_f32 v72, v70, s0
	v_lshl_add_u64 v[70:71], v[132:133], 1, v[66:67]
	global_store_short v[70:71], v72, off
	v_mul_f32_e32 v70, v105, v213
	s_and_saveexec_b64 s[4:5], s[42:43]
	s_cbranch_execz .LBB0_346
	ds_swizzle_b32 v71, v70 offset:swizzle(SWAP,16)
	s_waitcnt lgkmcnt(0)
	v_mul_f32_e32 v71, v215, v71
	v_cndmask_b32_e64 v71, v71, -v71, vcc
	v_fmac_f32_e32 v71, v214, v70
	v_mov_b32_e32 v70, v71
.LBB0_346:
	s_or_b64 exec, exec, s[4:5]
	v_mul_f32_e32 v70, 0x3e16c740, v70
	v_cvt_pk_bf16_f32 v70, v70, s0
	v_lshl_add_u64 v[66:67], v[136:137], 1, v[66:67]
	global_store_short v[66:67], v70, off offset:64
	v_mul_f32_e32 v70, v89, v213
	s_and_saveexec_b64 s[4:5], s[44:45]
	s_cbranch_execz .LBB0_348
	ds_swizzle_b32 v71, v70 offset:swizzle(SWAP,16)
	s_waitcnt lgkmcnt(0)
	v_mul_f32_e32 v71, v215, v71
	v_cndmask_b32_e64 v71, v71, -v71, vcc
	v_fmac_f32_e32 v71, v214, v70
	v_mov_b32_e32 v70, v71
.LBB0_348:
	s_or_b64 exec, exec, s[4:5]
	v_mul_f32_e32 v70, 0x3e16c740, v70
	v_cvt_pk_bf16_f32 v70, v70, s0
	v_mul_f32_e32 v0, v73, v213
	global_store_short v[66:67], v70, off offset:128
	s_and_saveexec_b64 s[4:5], s[46:47]
	s_cbranch_execz .LBB0_350
	ds_swizzle_b32 v70, v0 offset:swizzle(SWAP,16)
	s_waitcnt lgkmcnt(0)
	v_mul_f32_e32 v69, v215, v70
	v_cndmask_b32_e64 v69, v69, -v69, vcc
	v_fmac_f32_e32 v69, v214, v0
	v_mov_b32_e32 v0, v69
.LBB0_350:
	s_or_b64 exec, exec, s[4:5]
	v_mul_f32_e32 v0, 0x3e16c740, v0
	v_cvt_pk_bf16_f32 v0, v0, s0
	global_store_short v[66:67], v0, off offset:192
	v_or_b32_e32 v66, 16, v134
	v_ashrrev_i32_e32 v67, 31, v66
	v_lshl_add_u64 v[68:69], v[66:67], 2, s[28:29]
	global_load_dword v213, v[224:225], off offset:128
	global_load_dword v214, v[234:235], off
	global_load_dword v215, v[234:235], off offset:64
	v_add_u32_e32 v68, s13, v66
	v_ashrrev_i32_e32 v69, 31, v68
	v_lshlrev_b64 v[68:69], 7, v[68:69]
	v_lshl_add_u64 v[70:71], v[130:131], 0, v[68:69]
	s_waitcnt vmcnt(56)
	v_mul_f32_e32 v70, v122, v216
	s_and_saveexec_b64 s[4:5], s[40:41]
	s_cbranch_execz .LBB0_352
	ds_swizzle_b32 v67, v70 offset:swizzle(SWAP,16)
	s_waitcnt lgkmcnt(0)
	v_mul_f32_e32 v67, v218, v67
	v_cndmask_b32_e64 v67, v67, -v67, vcc
	v_fmac_f32_e32 v67, v217, v70
	v_mov_b32_e32 v70, v67
; __device__ __forceinline__ uint32_t pk2(float lo, float hi) { typedef float f2 __attribute__((ext_vector_type(2))); const f2 v = {lo, hi}; return __builtin_bit_cast(uint32_t, __builtin_convertvector(v, bf16x2_t)); }
; __device__ __forceinline__ void mla_up_tile(const Params& p, int b, int it, unsigned char* lds) {
;     ...
; #pragma unroll
;         for (int mi = 0; mi < 2; ++mi)
; #pragma unroll
;             for (int reg = 0; reg < 16; ++reg) {
;                 const int m = pm * 128 + wr * 64 + mi * 32 + (reg & 3) + 8 * (reg >> 2) + 4 * h;
;                 const float rq = RQ[m] ;
;                 const float* rp = rope + (size_t)(b * TH + m) * 32;
;                 const float cs = rp[r & 15], sn = rp[16 + (r & 15)];
; #pragma unroll
;                 for (int ni = 0; ni < 4; ++ni) {
;                     const int nb = pn * 256 + wc * 128 + ni * 32, n = nb + r;
;                     float v = acc[mi][ni][reg] * rq;
;                     if (((nb >> 5) % 3) == 2) {
;                         const float o = __builtin_bit_cast(float, __builtin_amdgcn_ds_swizzle(__builtin_bit_cast(int, v), 0x401f));
;                         v = (r < 16) ? (v * cs - o * sn) : (v * cs + o * sn);
;                     }
;                     QF[(size_t)m * 768 + n] = (bf16_t)(pk2(v * qsc, 0.f) & 0xffff);
.LBB0_352:
	s_or_b64 exec, exec, s[4:5]
	v_mov_b64_e32 v[72:73], s[34:35]
	v_mad_i64_i32 v[66:67], s[4:5], v66, s65, v[72:73]
	v_mul_f32_e32 v70, 0x3e16c740, v70
	v_cvt_pk_bf16_f32 v72, v70, s0
	v_lshl_add_u64 v[70:71], v[132:133], 1, v[66:67]
	global_store_short v[70:71], v72, off
	v_mul_f32_e32 v70, v106, v216
	s_and_saveexec_b64 s[4:5], s[42:43]
	s_cbranch_execz .LBB0_354
	ds_swizzle_b32 v71, v70 offset:swizzle(SWAP,16)
	s_waitcnt lgkmcnt(0)
	v_mul_f32_e32 v71, v218, v71
	v_cndmask_b32_e64 v71, v71, -v71, vcc
	v_fmac_f32_e32 v71, v217, v70
	v_mov_b32_e32 v70, v71
.LBB0_354:
	s_or_b64 exec, exec, s[4:5]
	v_mul_f32_e32 v70, 0x3e16c740, v70
	v_cvt_pk_bf16_f32 v70, v70, s0
	v_lshl_add_u64 v[66:67], v[136:137], 1, v[66:67]
	global_store_short v[66:67], v70, off offset:64
	v_mul_f32_e32 v70, v90, v216
	s_and_saveexec_b64 s[4:5], s[44:45]
	s_cbranch_execz .LBB0_356
	ds_swizzle_b32 v71, v70 offset:swizzle(SWAP,16)
	s_waitcnt lgkmcnt(0)
	v_mul_f32_e32 v71, v218, v71
	v_cndmask_b32_e64 v71, v71, -v71, vcc
	v_fmac_f32_e32 v71, v217, v70
	v_mov_b32_e32 v70, v71
.LBB0_356:
	s_or_b64 exec, exec, s[4:5]
	v_mul_f32_e32 v70, 0x3e16c740, v70
	v_cvt_pk_bf16_f32 v70, v70, s0
	v_mul_f32_e32 v0, v74, v216
	global_store_short v[66:67], v70, off offset:128
	s_and_saveexec_b64 s[4:5], s[46:47]
	s_cbranch_execz .LBB0_358
	ds_swizzle_b32 v70, v0 offset:swizzle(SWAP,16)
	s_waitcnt lgkmcnt(0)
	v_mul_f32_e32 v69, v218, v70
	v_cndmask_b32_e64 v69, v69, -v69, vcc
	v_fmac_f32_e32 v69, v217, v0
	v_mov_b32_e32 v0, v69
.LBB0_358:
	s_or_b64 exec, exec, s[4:5]
	v_mul_f32_e32 v0, 0x3e16c740, v0
	v_cvt_pk_bf16_f32 v0, v0, s0
	global_store_short v[66:67], v0, off offset:192
	v_or_b32_e32 v66, 17, v134
	v_ashrrev_i32_e32 v67, 31, v66
	v_lshl_add_u64 v[68:69], v[66:67], 2, s[28:29]
	global_load_dword v216, v[224:225], off offset:132
	global_load_dword v217, v[234:235], off offset:128
	global_load_dword v218, v[234:235], off offset:192
	v_add_u32_e32 v68, s13, v66
	v_ashrrev_i32_e32 v69, 31, v68
	v_lshlrev_b64 v[68:69], 7, v[68:69]
	v_lshl_add_u64 v[70:71], v[130:131], 0, v[68:69]
	s_waitcnt vmcnt(56)
	v_mul_f32_e32 v70, v123, v192
	s_and_saveexec_b64 s[4:5], s[40:41]
	s_cbranch_execz .LBB0_360
	ds_swizzle_b32 v67, v70 offset:swizzle(SWAP,16)
	s_waitcnt lgkmcnt(0)
	v_mul_f32_e32 v67, v194, v67
	v_cndmask_b32_e64 v67, v67, -v67, vcc
	v_fmac_f32_e32 v67, v193, v70
	v_mov_b32_e32 v70, v67
.LBB0_360:
	s_or_b64 exec, exec, s[4:5]
	v_mov_b64_e32 v[72:73], s[34:35]
	v_mad_i64_i32 v[66:67], s[4:5], v66, s65, v[72:73]
	v_mul_f32_e32 v70, 0x3e16c740, v70
	v_cvt_pk_bf16_f32 v72, v70, s0
	v_lshl_add_u64 v[70:71], v[132:133], 1, v[66:67]
	global_store_short v[70:71], v72, off
	v_mul_f32_e32 v70, v107, v192
	s_and_saveexec_b64 s[4:5], s[42:43]
	s_cbranch_execz .LBB0_362
	ds_swizzle_b32 v71, v70 offset:swizzle(SWAP,16)
	s_waitcnt lgkmcnt(0)
	v_mul_f32_e32 v71, v194, v71
	v_cndmask_b32_e64 v71, v71, -v71, vcc
	v_fmac_f32_e32 v71, v193, v70
	v_mov_b32_e32 v70, v71
.LBB0_362:
	s_or_b64 exec, exec, s[4:5]
	v_mul_f32_e32 v70, 0x3e16c740, v70
	v_cvt_pk_bf16_f32 v70, v70, s0
	v_lshl_add_u64 v[66:67], v[136:137], 1, v[66:67]
	global_store_short v[66:67], v70, off offset:64
	v_mul_f32_e32 v70, v91, v192
	s_and_saveexec_b64 s[4:5], s[44:45]
	s_cbranch_execz .LBB0_364
	ds_swizzle_b32 v71, v70 offset:swizzle(SWAP,16)
	s_waitcnt lgkmcnt(0)
	v_mul_f32_e32 v71, v194, v71
	v_cndmask_b32_e64 v71, v71, -v71, vcc
	v_fmac_f32_e32 v71, v193, v70
	v_mov_b32_e32 v70, v71
.LBB0_364:
	s_or_b64 exec, exec, s[4:5]
	v_mul_f32_e32 v70, 0x3e16c740, v70
	v_cvt_pk_bf16_f32 v70, v70, s0
	v_mul_f32_e32 v0, v75, v192
	global_store_short v[66:67], v70, off offset:128
	s_and_saveexec_b64 s[4:5], s[46:47]
	s_cbranch_execz .LBB0_366
	ds_swizzle_b32 v70, v0 offset:swizzle(SWAP,16)
	s_waitcnt lgkmcnt(0)
	v_mul_f32_e32 v69, v194, v70
	v_cndmask_b32_e64 v69, v69, -v69, vcc
	v_fmac_f32_e32 v69, v193, v0
	v_mov_b32_e32 v0, v69
.LBB0_366:
	s_or_b64 exec, exec, s[4:5]
	v_mul_f32_e32 v0, 0x3e16c740, v0
	v_cvt_pk_bf16_f32 v0, v0, s0
	global_store_short v[66:67], v0, off offset:192
	v_or_b32_e32 v66, 18, v134
	v_ashrrev_i32_e32 v67, 31, v66
	v_lshl_add_u64 v[68:69], v[66:67], 2, s[28:29]
	global_load_dword v192, v[224:225], off offset:136
	global_load_dword v193, v[234:235], off offset:256
	global_load_dword v194, v[234:235], off offset:320
	v_add_u32_e32 v68, s13, v66
	v_ashrrev_i32_e32 v69, 31, v68
	v_lshlrev_b64 v[68:69], 7, v[68:69]
	v_lshl_add_u64 v[70:71], v[130:131], 0, v[68:69]
	s_waitcnt vmcnt(56)
	v_mul_f32_e32 v70, v124, v195
	s_and_saveexec_b64 s[4:5], s[40:41]
	s_cbranch_execz .LBB0_368
	ds_swizzle_b32 v67, v70 offset:swizzle(SWAP,16)
	s_waitcnt lgkmcnt(0)
	v_mul_f32_e32 v67, v197, v67
	v_cndmask_b32_e64 v67, v67, -v67, vcc
	v_fmac_f32_e32 v67, v196, v70
	v_mov_b32_e32 v70, v67
.LBB0_368:
	s_or_b64 exec, exec, s[4:5]
	v_mov_b64_e32 v[72:73], s[34:35]
	v_mad_i64_i32 v[66:67], s[4:5], v66, s65, v[72:73]
	v_mul_f32_e32 v70, 0x3e16c740, v70
	v_cvt_pk_bf16_f32 v72, v70, s0
	v_lshl_add_u64 v[70:71], v[132:133], 1, v[66:67]
	global_store_short v[70:71], v72, off
	v_mul_f32_e32 v70, v108, v195
	s_and_saveexec_b64 s[4:5], s[42:43]
	s_cbranch_execz .LBB0_370
	ds_swizzle_b32 v71, v70 offset:swizzle(SWAP,16)
	s_waitcnt lgkmcnt(0)
	v_mul_f32_e32 v71, v197, v71
	v_cndmask_b32_e64 v71, v71, -v71, vcc
	v_fmac_f32_e32 v71, v196, v70
	v_mov_b32_e32 v70, v71
.LBB0_370:
	s_or_b64 exec, exec, s[4:5]
	v_mul_f32_e32 v70, 0x3e16c740, v70
	v_cvt_pk_bf16_f32 v70, v70, s0
	v_lshl_add_u64 v[66:67], v[136:137], 1, v[66:67]
	global_store_short v[66:67], v70, off offset:64
	v_mul_f32_e32 v70, v92, v195
	s_and_saveexec_b64 s[4:5], s[44:45]
	s_cbranch_execz .LBB0_372
	ds_swizzle_b32 v71, v70 offset:swizzle(SWAP,16)
	s_waitcnt lgkmcnt(0)
	v_mul_f32_e32 v71, v197, v71
	v_cndmask_b32_e64 v71, v71, -v71, vcc
	v_fmac_f32_e32 v71, v196, v70
	v_mov_b32_e32 v70, v71
; __device__ __forceinline__ uint32_t pk2(float lo, float hi) { typedef float f2 __attribute__((ext_vector_type(2))); const f2 v = {lo, hi}; return __builtin_bit_cast(uint32_t, __builtin_convertvector(v, bf16x2_t)); }
; __device__ __forceinline__ void mla_up_tile(const Params& p, int b, int it, unsigned char* lds) {
;     ...
; #pragma unroll
;         for (int mi = 0; mi < 2; ++mi)
; #pragma unroll
;             for (int reg = 0; reg < 16; ++reg) {
;                 const int m = pm * 128 + wr * 64 + mi * 32 + (reg & 3) + 8 * (reg >> 2) + 4 * h;
;                 const float rq = RQ[m] ;
;                 const float* rp = rope + (size_t)(b * TH + m) * 32;
;                 const float cs = rp[r & 15], sn = rp[16 + (r & 15)];
; #pragma unroll
;                 for (int ni = 0; ni < 4; ++ni) {
;                     const int nb = pn * 256 + wc * 128 + ni * 32, n = nb + r;
;                     float v = acc[mi][ni][reg] * rq;
;                     if (((nb >> 5) % 3) == 2) {
;                         const float o = __builtin_bit_cast(float, __builtin_amdgcn_ds_swizzle(__builtin_bit_cast(int, v), 0x401f));
;                         v = (r < 16) ? (v * cs - o * sn) : (v * cs + o * sn);
;                     }
;                     QF[(size_t)m * 768 + n] = (bf16_t)(pk2(v * qsc, 0.f) & 0xffff);
;                 }
;             }
.LBB0_372:
	s_or_b64 exec, exec, s[4:5]
	v_mul_f32_e32 v70, 0x3e16c740, v70
	v_cvt_pk_bf16_f32 v70, v70, s0
	v_mul_f32_e32 v0, v76, v195
	global_store_short v[66:67], v70, off offset:128
	s_and_saveexec_b64 s[4:5], s[46:47]
	s_cbranch_execz .LBB0_374
	ds_swizzle_b32 v70, v0 offset:swizzle(SWAP,16)
	s_waitcnt lgkmcnt(0)
	v_mul_f32_e32 v69, v197, v70
	v_cndmask_b32_e64 v69, v69, -v69, vcc
	v_fmac_f32_e32 v69, v196, v0
	v_mov_b32_e32 v0, v69
.LBB0_374:
	s_or_b64 exec, exec, s[4:5]
	v_mul_f32_e32 v0, 0x3e16c740, v0
	v_cvt_pk_bf16_f32 v0, v0, s0
	global_store_short v[66:67], v0, off offset:192
	v_or_b32_e32 v66, 19, v134
	v_ashrrev_i32_e32 v67, 31, v66
	v_lshl_add_u64 v[68:69], v[66:67], 2, s[28:29]
	global_load_dword v195, v[224:225], off offset:140
	global_load_dword v196, v[234:235], off offset:384
	global_load_dword v197, v[234:235], off offset:448
	v_add_u32_e32 v68, s13, v66
	v_ashrrev_i32_e32 v69, 31, v68
	v_lshlrev_b64 v[68:69], 7, v[68:69]
	v_lshl_add_u64 v[70:71], v[130:131], 0, v[68:69]
	s_waitcnt vmcnt(56)
	v_mul_f32_e32 v70, v125, v198
	s_and_saveexec_b64 s[4:5], s[40:41]
	s_cbranch_execz .LBB0_376
	ds_swizzle_b32 v67, v70 offset:swizzle(SWAP,16)
	s_waitcnt lgkmcnt(0)
	v_mul_f32_e32 v67, v200, v67
	v_cndmask_b32_e64 v67, v67, -v67, vcc
	v_fmac_f32_e32 v67, v199, v70
	v_mov_b32_e32 v70, v67
.LBB0_376:
	s_or_b64 exec, exec, s[4:5]
	v_mov_b64_e32 v[72:73], s[34:35]
	v_mad_i64_i32 v[66:67], s[4:5], v66, s65, v[72:73]
	v_mul_f32_e32 v70, 0x3e16c740, v70
	v_cvt_pk_bf16_f32 v72, v70, s0
	v_lshl_add_u64 v[70:71], v[132:133], 1, v[66:67]
	global_store_short v[70:71], v72, off
	v_mul_f32_e32 v70, v109, v198
	s_and_saveexec_b64 s[4:5], s[42:43]
	s_cbranch_execz .LBB0_378
	ds_swizzle_b32 v71, v70 offset:swizzle(SWAP,16)
	s_waitcnt lgkmcnt(0)
	v_mul_f32_e32 v71, v200, v71
	v_cndmask_b32_e64 v71, v71, -v71, vcc
	v_fmac_f32_e32 v71, v199, v70
	v_mov_b32_e32 v70, v71
.LBB0_378:
	s_or_b64 exec, exec, s[4:5]
	v_mul_f32_e32 v70, 0x3e16c740, v70
	v_cvt_pk_bf16_f32 v70, v70, s0
	v_lshl_add_u64 v[66:67], v[136:137], 1, v[66:67]
	global_store_short v[66:67], v70, off offset:64
	v_mul_f32_e32 v70, v93, v198
	s_and_saveexec_b64 s[4:5], s[44:45]
	s_cbranch_execz .LBB0_380
	ds_swizzle_b32 v71, v70 offset:swizzle(SWAP,16)
	s_waitcnt lgkmcnt(0)
	v_mul_f32_e32 v71, v200, v71
	v_cndmask_b32_e64 v71, v71, -v71, vcc
	v_fmac_f32_e32 v71, v199, v70
	v_mov_b32_e32 v70, v71
.LBB0_380:
	s_or_b64 exec, exec, s[4:5]
	v_mul_f32_e32 v70, 0x3e16c740, v70
	v_cvt_pk_bf16_f32 v70, v70, s0
	v_mul_f32_e32 v0, v77, v198
	global_store_short v[66:67], v70, off offset:128
	s_and_saveexec_b64 s[4:5], s[46:47]
	s_cbranch_execz .LBB0_382
	ds_swizzle_b32 v70, v0 offset:swizzle(SWAP,16)
	s_waitcnt lgkmcnt(0)
	v_mul_f32_e32 v69, v200, v70
	v_cndmask_b32_e64 v69, v69, -v69, vcc
	v_fmac_f32_e32 v69, v199, v0
	v_mov_b32_e32 v0, v69
.LBB0_382:
	s_or_b64 exec, exec, s[4:5]
	v_mul_f32_e32 v0, 0x3e16c740, v0
	v_cvt_pk_bf16_f32 v0, v0, s0
	global_store_short v[66:67], v0, off offset:192
	v_or_b32_e32 v66, 24, v134
	v_ashrrev_i32_e32 v67, 31, v66
	v_lshl_add_u64 v[68:69], v[66:67], 2, s[28:29]
	global_load_dword v198, v[224:225], off offset:160
	global_load_dword v199, v[234:235], off offset:1024
	global_load_dword v200, v[234:235], off offset:1088
	v_add_u32_e32 v68, s13, v66
	v_ashrrev_i32_e32 v69, 31, v68
	v_lshlrev_b64 v[68:69], 7, v[68:69]
	v_lshl_add_u64 v[70:71], v[130:131], 0, v[68:69]
	s_waitcnt vmcnt(56)
	v_mul_f32_e32 v70, v126, v201
	s_and_saveexec_b64 s[4:5], s[40:41]
	s_cbranch_execz .LBB0_384
	ds_swizzle_b32 v67, v70 offset:swizzle(SWAP,16)
	s_waitcnt lgkmcnt(0)
	v_mul_f32_e32 v67, v203, v67
	v_cndmask_b32_e64 v67, v67, -v67, vcc
	v_fmac_f32_e32 v67, v202, v70
	v_mov_b32_e32 v70, v67
.LBB0_384:
	s_or_b64 exec, exec, s[4:5]
	v_mov_b64_e32 v[72:73], s[34:35]
	v_mad_i64_i32 v[66:67], s[4:5], v66, s65, v[72:73]
	v_mul_f32_e32 v70, 0x3e16c740, v70
	v_cvt_pk_bf16_f32 v72, v70, s0
	v_lshl_add_u64 v[70:71], v[132:133], 1, v[66:67]
	global_store_short v[70:71], v72, off
	v_mul_f32_e32 v70, v110, v201
	s_and_saveexec_b64 s[4:5], s[42:43]
	s_cbranch_execz .LBB0_386
	ds_swizzle_b32 v71, v70 offset:swizzle(SWAP,16)
	s_waitcnt lgkmcnt(0)
	v_mul_f32_e32 v71, v203, v71
	v_cndmask_b32_e64 v71, v71, -v71, vcc
	v_fmac_f32_e32 v71, v202, v70
	v_mov_b32_e32 v70, v71
.LBB0_386:
	s_or_b64 exec, exec, s[4:5]
	v_mul_f32_e32 v70, 0x3e16c740, v70
	v_cvt_pk_bf16_f32 v70, v70, s0
	v_lshl_add_u64 v[66:67], v[136:137], 1, v[66:67]
	global_store_short v[66:67], v70, off offset:64
	v_mul_f32_e32 v70, v94, v201
	s_and_saveexec_b64 s[4:5], s[44:45]
	s_cbranch_execz .LBB0_388
	ds_swizzle_b32 v71, v70 offset:swizzle(SWAP,16)
	s_waitcnt lgkmcnt(0)
	v_mul_f32_e32 v71, v203, v71
	v_cndmask_b32_e64 v71, v71, -v71, vcc
	v_fmac_f32_e32 v71, v202, v70
	v_mov_b32_e32 v70, v71
.LBB0_388:
	s_or_b64 exec, exec, s[4:5]
	v_mul_f32_e32 v70, 0x3e16c740, v70
	v_cvt_pk_bf16_f32 v70, v70, s0
	v_mul_f32_e32 v0, v78, v201
	global_store_short v[66:67], v70, off offset:128
	s_and_saveexec_b64 s[4:5], s[46:47]
	s_cbranch_execz .LBB0_390
	ds_swizzle_b32 v70, v0 offset:swizzle(SWAP,16)
	s_waitcnt lgkmcnt(0)
	v_mul_f32_e32 v69, v203, v70
	v_cndmask_b32_e64 v69, v69, -v69, vcc
	v_fmac_f32_e32 v69, v202, v0
	v_mov_b32_e32 v0, v69
; __device__ __forceinline__ uint32_t pk2(float lo, float hi) { typedef float f2 __attribute__((ext_vector_type(2))); const f2 v = {lo, hi}; return __builtin_bit_cast(uint32_t, __builtin_convertvector(v, bf16x2_t)); }
; __device__ __forceinline__ void mla_up_tile(const Params& p, int b, int it, unsigned char* lds) {
;     ...
; #pragma unroll
;         for (int mi = 0; mi < 2; ++mi)
; #pragma unroll
;             for (int reg = 0; reg < 16; ++reg) {
;                 const int m = pm * 128 + wr * 64 + mi * 32 + (reg & 3) + 8 * (reg >> 2) + 4 * h;
;                 const float rq = RQ[m] ;
;                 const float* rp = rope + (size_t)(b * TH + m) * 32;
;                 const float cs = rp[r & 15], sn = rp[16 + (r & 15)];
; #pragma unroll
;                 for (int ni = 0; ni < 4; ++ni) {
;                     const int nb = pn * 256 + wc * 128 + ni * 32, n = nb + r;
;                     float v = acc[mi][ni][reg] * rq;
;                     if (((nb >> 5) % 3) == 2) {
;                         const float o = __builtin_bit_cast(float, __builtin_amdgcn_ds_swizzle(__builtin_bit_cast(int, v), 0x401f));
;                         v = (r < 16) ? (v * cs - o * sn) : (v * cs + o * sn);
;                     }
;                     QF[(size_t)m * 768 + n] = (bf16_t)(pk2(v * qsc, 0.f) & 0xffff);
;                 }
;             }
.LBB0_390:
	s_or_b64 exec, exec, s[4:5]
	v_mul_f32_e32 v0, 0x3e16c740, v0
	v_cvt_pk_bf16_f32 v0, v0, s0
	global_store_short v[66:67], v0, off offset:192
	v_or_b32_e32 v66, 25, v134
	v_ashrrev_i32_e32 v67, 31, v66
	v_lshl_add_u64 v[68:69], v[66:67], 2, s[28:29]
	global_load_dword v201, v[224:225], off offset:164
	global_load_dword v202, v[234:235], off offset:1152
	global_load_dword v203, v[234:235], off offset:1216
	v_add_u32_e32 v68, s13, v66
	v_ashrrev_i32_e32 v69, 31, v68
	v_lshlrev_b64 v[68:69], 7, v[68:69]
	v_lshl_add_u64 v[70:71], v[130:131], 0, v[68:69]
	s_waitcnt vmcnt(56)
	v_mul_f32_e32 v70, v127, v204
	s_and_saveexec_b64 s[4:5], s[40:41]
	s_cbranch_execz .LBB0_392
	ds_swizzle_b32 v67, v70 offset:swizzle(SWAP,16)
	s_waitcnt lgkmcnt(0)
	v_mul_f32_e32 v67, v206, v67
	v_cndmask_b32_e64 v67, v67, -v67, vcc
	v_fmac_f32_e32 v67, v205, v70
	v_mov_b32_e32 v70, v67
.LBB0_392:
	s_or_b64 exec, exec, s[4:5]
	v_mov_b64_e32 v[72:73], s[34:35]
	v_mad_i64_i32 v[66:67], s[4:5], v66, s65, v[72:73]
	v_mul_f32_e32 v70, 0x3e16c740, v70
	v_cvt_pk_bf16_f32 v72, v70, s0
	v_lshl_add_u64 v[70:71], v[132:133], 1, v[66:67]
	global_store_short v[70:71], v72, off
	v_mul_f32_e32 v70, v111, v204
	s_and_saveexec_b64 s[4:5], s[42:43]
	s_cbranch_execz .LBB0_394
	ds_swizzle_b32 v71, v70 offset:swizzle(SWAP,16)
	s_waitcnt lgkmcnt(0)
	v_mul_f32_e32 v71, v206, v71
	v_cndmask_b32_e64 v71, v71, -v71, vcc
	v_fmac_f32_e32 v71, v205, v70
	v_mov_b32_e32 v70, v71
.LBB0_394:
	s_or_b64 exec, exec, s[4:5]
	v_mul_f32_e32 v70, 0x3e16c740, v70
	v_cvt_pk_bf16_f32 v70, v70, s0
	v_lshl_add_u64 v[66:67], v[136:137], 1, v[66:67]
	global_store_short v[66:67], v70, off offset:64
	v_mul_f32_e32 v70, v95, v204
	s_and_saveexec_b64 s[4:5], s[44:45]
	s_cbranch_execz .LBB0_396
	ds_swizzle_b32 v71, v70 offset:swizzle(SWAP,16)
	s_waitcnt lgkmcnt(0)
	v_mul_f32_e32 v71, v206, v71
	v_cndmask_b32_e64 v71, v71, -v71, vcc
	v_fmac_f32_e32 v71, v205, v70
	v_mov_b32_e32 v70, v71
.LBB0_396:
	s_or_b64 exec, exec, s[4:5]
	v_mul_f32_e32 v70, 0x3e16c740, v70
	v_cvt_pk_bf16_f32 v70, v70, s0
	v_mul_f32_e32 v0, v79, v204
	global_store_short v[66:67], v70, off offset:128
	s_and_saveexec_b64 s[4:5], s[46:47]
	s_cbranch_execz .LBB0_398
	ds_swizzle_b32 v70, v0 offset:swizzle(SWAP,16)
	s_waitcnt lgkmcnt(0)
	v_mul_f32_e32 v69, v206, v70
	v_cndmask_b32_e64 v69, v69, -v69, vcc
	v_fmac_f32_e32 v69, v205, v0
	v_mov_b32_e32 v0, v69
.LBB0_398:
	s_or_b64 exec, exec, s[4:5]
	v_mul_f32_e32 v0, 0x3e16c740, v0
	v_cvt_pk_bf16_f32 v0, v0, s0
	global_store_short v[66:67], v0, off offset:192
	v_or_b32_e32 v66, 26, v134
	v_ashrrev_i32_e32 v67, 31, v66
	v_lshl_add_u64 v[68:69], v[66:67], 2, s[28:29]
	global_load_dword v204, v[224:225], off offset:168
	global_load_dword v205, v[234:235], off offset:1280
	global_load_dword v206, v[234:235], off offset:1344
	v_add_u32_e32 v68, s13, v66
	v_ashrrev_i32_e32 v69, 31, v68
	v_lshlrev_b64 v[68:69], 7, v[68:69]
	v_lshl_add_u64 v[70:71], v[130:131], 0, v[68:69]
	s_waitcnt vmcnt(56)
	v_mul_f32_e32 v70, v128, v207
	s_and_saveexec_b64 s[4:5], s[40:41]
	s_cbranch_execz .LBB0_400
	ds_swizzle_b32 v67, v70 offset:swizzle(SWAP,16)
	s_waitcnt lgkmcnt(0)
	v_mul_f32_e32 v67, v209, v67
	v_cndmask_b32_e64 v67, v67, -v67, vcc
	v_fmac_f32_e32 v67, v208, v70
	v_mov_b32_e32 v70, v67
.LBB0_400:
	s_or_b64 exec, exec, s[4:5]
	v_mov_b64_e32 v[72:73], s[34:35]
	v_mad_i64_i32 v[66:67], s[4:5], v66, s65, v[72:73]
	v_mul_f32_e32 v70, 0x3e16c740, v70
	v_cvt_pk_bf16_f32 v72, v70, s0
	v_lshl_add_u64 v[70:71], v[132:133], 1, v[66:67]
	global_store_short v[70:71], v72, off
	v_mul_f32_e32 v70, v112, v207
	s_and_saveexec_b64 s[4:5], s[42:43]
	s_cbranch_execz .LBB0_402
	ds_swizzle_b32 v71, v70 offset:swizzle(SWAP,16)
	s_waitcnt lgkmcnt(0)
	v_mul_f32_e32 v71, v209, v71
	v_cndmask_b32_e64 v71, v71, -v71, vcc
	v_fmac_f32_e32 v71, v208, v70
	v_mov_b32_e32 v70, v71
.LBB0_402:
	s_or_b64 exec, exec, s[4:5]
	v_mul_f32_e32 v70, 0x3e16c740, v70
	v_cvt_pk_bf16_f32 v70, v70, s0
	v_lshl_add_u64 v[66:67], v[136:137], 1, v[66:67]
	global_store_short v[66:67], v70, off offset:64
	v_mul_f32_e32 v70, v96, v207
	s_and_saveexec_b64 s[4:5], s[44:45]
	s_cbranch_execz .LBB0_404
	ds_swizzle_b32 v71, v70 offset:swizzle(SWAP,16)
	s_waitcnt lgkmcnt(0)
	v_mul_f32_e32 v71, v209, v71
	v_cndmask_b32_e64 v71, v71, -v71, vcc
	v_fmac_f32_e32 v71, v208, v70
	v_mov_b32_e32 v70, v71
.LBB0_404:
	s_or_b64 exec, exec, s[4:5]
	v_mul_f32_e32 v70, 0x3e16c740, v70
	v_cvt_pk_bf16_f32 v70, v70, s0
	v_mul_f32_e32 v0, v80, v207
	global_store_short v[66:67], v70, off offset:128
	s_and_saveexec_b64 s[4:5], s[46:47]
	s_cbranch_execz .LBB0_406
	ds_swizzle_b32 v70, v0 offset:swizzle(SWAP,16)
	s_waitcnt lgkmcnt(0)
	v_mul_f32_e32 v69, v209, v70
	v_cndmask_b32_e64 v69, v69, -v69, vcc
	v_fmac_f32_e32 v69, v208, v0
	v_mov_b32_e32 v0, v69
.LBB0_406:
	s_or_b64 exec, exec, s[4:5]
	v_mul_f32_e32 v0, 0x3e16c740, v0
	v_cvt_pk_bf16_f32 v0, v0, s0
	global_store_short v[66:67], v0, off offset:192
	v_or_b32_e32 v66, 27, v134
	v_ashrrev_i32_e32 v67, 31, v66
	v_lshl_add_u64 v[68:69], v[66:67], 2, s[28:29]
	global_load_dword v207, v[224:225], off offset:172
	global_load_dword v208, v[234:235], off offset:1408
	global_load_dword v209, v[234:235], off offset:1472
	v_add_u32_e32 v68, s13, v66
	v_ashrrev_i32_e32 v69, 31, v68
	v_lshlrev_b64 v[68:69], 7, v[68:69]
	v_lshl_add_u64 v[70:71], v[130:131], 0, v[68:69]
	s_waitcnt vmcnt(56)
	v_mul_f32_e32 v70, v129, v210
	s_and_saveexec_b64 s[4:5], s[40:41]
	s_cbranch_execz .LBB0_408
	ds_swizzle_b32 v67, v70 offset:swizzle(SWAP,16)
	s_waitcnt lgkmcnt(0)
	v_mul_f32_e32 v67, v212, v67
	v_cndmask_b32_e64 v67, v67, -v67, vcc
	v_fmac_f32_e32 v67, v211, v70
	v_mov_b32_e32 v70, v67
; __device__ __forceinline__ uint32_t pk2(float lo, float hi) { typedef float f2 __attribute__((ext_vector_type(2))); const f2 v = {lo, hi}; return __builtin_bit_cast(uint32_t, __builtin_convertvector(v, bf16x2_t)); }
; __device__ __forceinline__ void mla_up_tile(const Params& p, int b, int it, unsigned char* lds) {
;     ...
; #pragma unroll
;         for (int mi = 0; mi < 2; ++mi)
; #pragma unroll
;             for (int reg = 0; reg < 16; ++reg) {
;                 const int m = pm * 128 + wr * 64 + mi * 32 + (reg & 3) + 8 * (reg >> 2) + 4 * h;
;                 const float rq = RQ[m] ;
;                 const float* rp = rope + (size_t)(b * TH + m) * 32;
;                 const float cs = rp[r & 15], sn = rp[16 + (r & 15)];
; #pragma unroll
;                 for (int ni = 0; ni < 4; ++ni) {
;                     const int nb = pn * 256 + wc * 128 + ni * 32, n = nb + r;
;                     float v = acc[mi][ni][reg] * rq;
;                     if (((nb >> 5) % 3) == 2) {
;                         const float o = __builtin_bit_cast(float, __builtin_amdgcn_ds_swizzle(__builtin_bit_cast(int, v), 0x401f));
;                         v = (r < 16) ? (v * cs - o * sn) : (v * cs + o * sn);
;                     }
;                     QF[(size_t)m * 768 + n] = (bf16_t)(pk2(v * qsc, 0.f) & 0xffff);
;                 }
;             }
.LBB0_408:
	s_or_b64 exec, exec, s[4:5]
	v_mov_b64_e32 v[72:73], s[34:35]
	v_mad_i64_i32 v[66:67], s[4:5], v66, s65, v[72:73]
	v_mul_f32_e32 v70, 0x3e16c740, v70
	v_cvt_pk_bf16_f32 v72, v70, s0
	v_lshl_add_u64 v[70:71], v[132:133], 1, v[66:67]
	global_store_short v[70:71], v72, off
	v_mul_f32_e32 v70, v113, v210
	s_and_saveexec_b64 s[4:5], s[42:43]
	s_cbranch_execz .LBB0_410
	ds_swizzle_b32 v71, v70 offset:swizzle(SWAP,16)
	s_waitcnt lgkmcnt(0)
	v_mul_f32_e32 v71, v212, v71
	v_cndmask_b32_e64 v71, v71, -v71, vcc
	v_fmac_f32_e32 v71, v211, v70
	v_mov_b32_e32 v70, v71
.LBB0_410:
	s_or_b64 exec, exec, s[4:5]
	v_mul_f32_e32 v70, 0x3e16c740, v70
	v_cvt_pk_bf16_f32 v70, v70, s0
	v_lshl_add_u64 v[66:67], v[136:137], 1, v[66:67]
	global_store_short v[66:67], v70, off offset:64
	v_mul_f32_e32 v70, v97, v210
	s_and_saveexec_b64 s[4:5], s[44:45]
	s_cbranch_execz .LBB0_412
	ds_swizzle_b32 v71, v70 offset:swizzle(SWAP,16)
	s_waitcnt lgkmcnt(0)
	v_mul_f32_e32 v71, v212, v71
	v_cndmask_b32_e64 v71, v71, -v71, vcc
	v_fmac_f32_e32 v71, v211, v70
	v_mov_b32_e32 v70, v71
.LBB0_412:
	s_or_b64 exec, exec, s[4:5]
	v_mul_f32_e32 v70, 0x3e16c740, v70
	v_cvt_pk_bf16_f32 v70, v70, s0
	v_mul_f32_e32 v0, v81, v210
	global_store_short v[66:67], v70, off offset:128
	s_and_saveexec_b64 s[4:5], s[46:47]
	s_cbranch_execz .LBB0_414
	ds_swizzle_b32 v70, v0 offset:swizzle(SWAP,16)
	s_waitcnt lgkmcnt(0)
	v_mul_f32_e32 v69, v212, v70
	v_cndmask_b32_e64 v69, v69, -v69, vcc
	v_fmac_f32_e32 v69, v211, v0
	v_mov_b32_e32 v0, v69
.LBB0_414:
	s_or_b64 exec, exec, s[4:5]
	v_mul_f32_e32 v0, 0x3e16c740, v0
	v_cvt_pk_bf16_f32 v0, v0, s0
	global_store_short v[66:67], v0, off offset:192
	v_or_b32_e32 v66, 32, v134
	v_ashrrev_i32_e32 v67, 31, v66
	v_lshl_add_u64 v[68:69], v[66:67], 2, s[28:29]
	global_load_dword v210, v[224:225], off offset:192
	global_load_dword v211, v[234:235], off offset:2048
	global_load_dword v212, v[234:235], off offset:2112
	v_add_u32_e32 v68, s13, v66
	v_ashrrev_i32_e32 v69, 31, v68
	v_lshlrev_b64 v[68:69], 7, v[68:69]
	v_lshl_add_u64 v[70:71], v[130:131], 0, v[68:69]
	s_waitcnt vmcnt(56)
	v_mul_f32_e32 v50, v50, v213
	s_and_saveexec_b64 s[4:5], s[40:41]
	s_cbranch_execz .LBB0_416
	ds_swizzle_b32 v67, v50 offset:swizzle(SWAP,16)
	s_waitcnt lgkmcnt(0)
	v_mul_f32_e32 v67, v215, v67
	v_cndmask_b32_e64 v67, v67, -v67, vcc
	v_fmac_f32_e32 v67, v214, v50
	v_mov_b32_e32 v50, v67
.LBB0_416:
	s_or_b64 exec, exec, s[4:5]
	v_mov_b64_e32 v[70:71], s[34:35]
	v_mad_i64_i32 v[66:67], s[4:5], v66, s65, v[70:71]
	v_mul_f32_e32 v50, 0x3e16c740, v50
	v_cvt_pk_bf16_f32 v50, v50, s0
	v_lshl_add_u64 v[70:71], v[132:133], 1, v[66:67]
	v_mul_f32_e32 v34, v34, v213
	global_store_short v[70:71], v50, off
	s_and_saveexec_b64 s[4:5], s[42:43]
	s_cbranch_execz .LBB0_418
	ds_swizzle_b32 v50, v34 offset:swizzle(SWAP,16)
	s_waitcnt lgkmcnt(0)
	v_mul_f32_e32 v50, v215, v50
	v_cndmask_b32_e64 v50, v50, -v50, vcc
	v_fmac_f32_e32 v50, v214, v34
	v_mov_b32_e32 v34, v50
.LBB0_418:
	s_or_b64 exec, exec, s[4:5]
	v_mul_f32_e32 v34, 0x3e16c740, v34
	v_cvt_pk_bf16_f32 v34, v34, s0
	v_lshl_add_u64 v[66:67], v[136:137], 1, v[66:67]
	v_mul_f32_e32 v18, v18, v213
	global_store_short v[66:67], v34, off offset:64
	s_and_saveexec_b64 s[4:5], s[44:45]
	s_cbranch_execz .LBB0_420
	ds_swizzle_b32 v34, v18 offset:swizzle(SWAP,16)
	s_waitcnt lgkmcnt(0)
	v_mul_f32_e32 v34, v215, v34
	v_cndmask_b32_e64 v34, v34, -v34, vcc
	v_fmac_f32_e32 v34, v214, v18
	v_mov_b32_e32 v18, v34
.LBB0_420:
	s_or_b64 exec, exec, s[4:5]
	v_mul_f32_e32 v18, 0x3e16c740, v18
	v_cvt_pk_bf16_f32 v18, v18, s0
	v_mul_f32_e32 v0, v2, v213
	global_store_short v[66:67], v18, off offset:128
	s_and_saveexec_b64 s[4:5], s[46:47]
	s_cbranch_execz .LBB0_422
	ds_swizzle_b32 v2, v0 offset:swizzle(SWAP,16)
	s_waitcnt lgkmcnt(0)
	v_mul_f32_e32 v2, v215, v2
	v_cndmask_b32_e64 v2, v2, -v2, vcc
	v_fmac_f32_e32 v2, v214, v0
	v_mov_b32_e32 v0, v2
.LBB0_422:
	s_or_b64 exec, exec, s[4:5]
	v_mul_f32_e32 v0, 0x3e16c740, v0
	v_cvt_pk_bf16_f32 v0, v0, s0
	global_store_short v[66:67], v0, off offset:192
	v_or_b32_e32 v66, 33, v134
	v_ashrrev_i32_e32 v67, 31, v66
	v_lshl_add_u64 v[68:69], v[66:67], 2, s[28:29]
	global_load_dword v213, v[224:225], off offset:196
	global_load_dword v214, v[234:235], off offset:2176
	global_load_dword v215, v[234:235], off offset:2240
	v_add_u32_e32 v68, s13, v66
	v_ashrrev_i32_e32 v69, 31, v68
	v_lshlrev_b64 v[68:69], 7, v[68:69]
	v_lshl_add_u64 v[68:69], v[130:131], 0, v[68:69]
	s_waitcnt vmcnt(56)
	v_mul_f32_e32 v34, v51, v216
	s_and_saveexec_b64 s[4:5], s[40:41]
	s_cbranch_execz .LBB0_424
	ds_swizzle_b32 v50, v34 offset:swizzle(SWAP,16)
	s_waitcnt lgkmcnt(0)
	v_mul_f32_e32 v50, v218, v50
	v_cndmask_b32_e64 v50, v50, -v50, vcc
	v_fmac_f32_e32 v50, v217, v34
	v_mov_b32_e32 v34, v50
.LBB0_424:
	s_or_b64 exec, exec, s[4:5]
	v_mov_b64_e32 v[50:51], s[34:35]
	v_mad_i64_i32 v[50:51], s[4:5], v66, s65, v[50:51]
	v_mul_f32_e32 v34, 0x3e16c740, v34
	v_cvt_pk_bf16_f32 v34, v34, s0
	v_lshl_add_u64 v[66:67], v[132:133], 1, v[50:51]
	global_store_short v[66:67], v34, off
	v_mul_f32_e32 v34, v35, v216
	s_and_saveexec_b64 s[4:5], s[42:43]
	s_cbranch_execz .LBB0_426
	ds_swizzle_b32 v35, v34 offset:swizzle(SWAP,16)
	s_waitcnt lgkmcnt(0)
	v_mul_f32_e32 v35, v218, v35
	v_cndmask_b32_e64 v35, v35, -v35, vcc
	v_fmac_f32_e32 v35, v217, v34
	v_mov_b32_e32 v34, v35
.LBB0_426:
	s_or_b64 exec, exec, s[4:5]
	v_mul_f32_e32 v34, 0x3e16c740, v34
	v_cvt_pk_bf16_f32 v66, v34, s0
	v_lshl_add_u64 v[34:35], v[136:137], 1, v[50:51]
	v_mul_f32_e32 v19, v19, v216
	global_store_short v[34:35], v66, off offset:64
	s_and_saveexec_b64 s[4:5], s[44:45]
	s_cbranch_execz .LBB0_428
	ds_swizzle_b32 v50, v19 offset:swizzle(SWAP,16)
	s_waitcnt lgkmcnt(0)
	v_mul_f32_e32 v50, v218, v50
	v_cndmask_b32_e64 v50, v50, -v50, vcc
	v_fmac_f32_e32 v50, v217, v19
	v_mov_b32_e32 v19, v50
; __device__ __forceinline__ uint32_t pk2(float lo, float hi) { typedef float f2 __attribute__((ext_vector_type(2))); const f2 v = {lo, hi}; return __builtin_bit_cast(uint32_t, __builtin_convertvector(v, bf16x2_t)); }
; __device__ __forceinline__ void mla_up_tile(const Params& p, int b, int it, unsigned char* lds) {
;     ...
; #pragma unroll
;         for (int mi = 0; mi < 2; ++mi)
; #pragma unroll
;             for (int reg = 0; reg < 16; ++reg) {
;                 const int m = pm * 128 + wr * 64 + mi * 32 + (reg & 3) + 8 * (reg >> 2) + 4 * h;
;                 const float rq = RQ[m] ;
;                 const float* rp = rope + (size_t)(b * TH + m) * 32;
;                 const float cs = rp[r & 15], sn = rp[16 + (r & 15)];
; #pragma unroll
;                 for (int ni = 0; ni < 4; ++ni) {
;                     const int nb = pn * 256 + wc * 128 + ni * 32, n = nb + r;
;                     float v = acc[mi][ni][reg] * rq;
;                     if (((nb >> 5) % 3) == 2) {
;                         const float o = __builtin_bit_cast(float, __builtin_amdgcn_ds_swizzle(__builtin_bit_cast(int, v), 0x401f));
;                         v = (r < 16) ? (v * cs - o * sn) : (v * cs + o * sn);
;                     }
;                     QF[(size_t)m * 768 + n] = (bf16_t)(pk2(v * qsc, 0.f) & 0xffff);
;                 }
;             }
.LBB0_428:
	s_or_b64 exec, exec, s[4:5]
	v_mul_f32_e32 v19, 0x3e16c740, v19
	v_cvt_pk_bf16_f32 v19, v19, s0
	v_mul_f32_e32 v0, v3, v216
	global_store_short v[34:35], v19, off offset:128
	s_and_saveexec_b64 s[4:5], s[46:47]
	s_cbranch_execz .LBB0_430
	ds_swizzle_b32 v3, v0 offset:swizzle(SWAP,16)
	s_waitcnt lgkmcnt(0)
	v_mul_f32_e32 v3, v218, v3
	v_cndmask_b32_e64 v3, v3, -v3, vcc
	v_fmac_f32_e32 v3, v217, v0
	v_mov_b32_e32 v0, v3
.LBB0_430:
	s_or_b64 exec, exec, s[4:5]
	v_or_b32_e32 v2, 34, v134
	v_mul_f32_e32 v0, 0x3e16c740, v0
	v_ashrrev_i32_e32 v3, 31, v2
	v_cvt_pk_bf16_f32 v0, v0, s0
	v_lshl_add_u64 v[18:19], v[2:3], 2, s[28:29]
	global_store_short v[34:35], v0, off offset:192
	global_load_dword v216, v[224:225], off offset:200
	global_load_dword v217, v[234:235], off offset:2304
	global_load_dword v218, v[234:235], off offset:2368
	v_add_u32_e32 v18, s13, v2
	v_ashrrev_i32_e32 v19, 31, v18
	v_lshlrev_b64 v[18:19], 7, v[18:19]
	v_lshl_add_u64 v[34:35], v[130:131], 0, v[18:19]
	s_waitcnt vmcnt(56)
	v_mul_f32_e32 v34, v52, v192
	s_and_saveexec_b64 s[4:5], s[40:41]
	s_cbranch_execz .LBB0_432
	ds_swizzle_b32 v3, v34 offset:swizzle(SWAP,16)
	s_waitcnt lgkmcnt(0)
	v_mul_f32_e32 v3, v194, v3
	v_cndmask_b32_e64 v3, v3, -v3, vcc
	v_fmac_f32_e32 v3, v193, v34
	v_mov_b32_e32 v34, v3
.LBB0_432:
	s_or_b64 exec, exec, s[4:5]
	v_mov_b64_e32 v[50:51], s[34:35]
	v_mad_i64_i32 v[2:3], s[4:5], v2, s65, v[50:51]
	v_mul_f32_e32 v34, 0x3e16c740, v34
	v_cvt_pk_bf16_f32 v50, v34, s0
	v_lshl_add_u64 v[34:35], v[132:133], 1, v[2:3]
	global_store_short v[34:35], v50, off
	v_mul_f32_e32 v34, v36, v192
	s_and_saveexec_b64 s[4:5], s[42:43]
	s_cbranch_execz .LBB0_434
	ds_swizzle_b32 v35, v34 offset:swizzle(SWAP,16)
	s_waitcnt lgkmcnt(0)
	v_mul_f32_e32 v35, v194, v35
	v_cndmask_b32_e64 v35, v35, -v35, vcc
	v_fmac_f32_e32 v35, v193, v34
	v_mov_b32_e32 v34, v35
.LBB0_434:
	s_or_b64 exec, exec, s[4:5]
	v_mul_f32_e32 v34, 0x3e16c740, v34
	v_cvt_pk_bf16_f32 v34, v34, s0
	v_lshl_add_u64 v[2:3], v[136:137], 1, v[2:3]
	v_mul_f32_e32 v20, v20, v192
	global_store_short v[2:3], v34, off offset:64
	s_and_saveexec_b64 s[4:5], s[44:45]
	s_cbranch_execz .LBB0_436
	ds_swizzle_b32 v34, v20 offset:swizzle(SWAP,16)
	s_waitcnt lgkmcnt(0)
	v_mul_f32_e32 v34, v194, v34
	v_cndmask_b32_e64 v34, v34, -v34, vcc
	v_fmac_f32_e32 v34, v193, v20
	v_mov_b32_e32 v20, v34
.LBB0_436:
	s_or_b64 exec, exec, s[4:5]
	v_mul_f32_e32 v20, 0x3e16c740, v20
	v_cvt_pk_bf16_f32 v20, v20, s0
	v_mul_f32_e32 v0, v4, v192
	global_store_short v[2:3], v20, off offset:128
	s_and_saveexec_b64 s[4:5], s[46:47]
	s_cbranch_execz .LBB0_438
	ds_swizzle_b32 v4, v0 offset:swizzle(SWAP,16)
	s_waitcnt lgkmcnt(0)
	v_mul_f32_e32 v4, v194, v4
	v_cndmask_b32_e64 v4, v4, -v4, vcc
	v_fmac_f32_e32 v4, v193, v0
	v_mov_b32_e32 v0, v4
.LBB0_438:
	s_or_b64 exec, exec, s[4:5]
	v_mul_f32_e32 v0, 0x3e16c740, v0
	v_cvt_pk_bf16_f32 v0, v0, s0
	global_store_short v[2:3], v0, off offset:192
	v_or_b32_e32 v2, 35, v134
	v_ashrrev_i32_e32 v3, 31, v2
	v_lshl_add_u64 v[18:19], v[2:3], 2, s[28:29]
	global_load_dword v192, v[224:225], off offset:204
	global_load_dword v193, v[234:235], off offset:2432
	global_load_dword v194, v[234:235], off offset:2496
	v_add_u32_e32 v18, s13, v2
	v_ashrrev_i32_e32 v19, 31, v18
	v_lshlrev_b64 v[18:19], 7, v[18:19]
	v_lshl_add_u64 v[18:19], v[130:131], 0, v[18:19]
	s_nop 0
	s_waitcnt vmcnt(56)
	v_mul_f32_e32 v19, v53, v195
	s_and_saveexec_b64 s[4:5], s[40:41]
	s_cbranch_execz .LBB0_440
	ds_swizzle_b32 v3, v19 offset:swizzle(SWAP,16)
	s_waitcnt lgkmcnt(0)
	v_mul_f32_e32 v3, v197, v3
	v_cndmask_b32_e64 v3, v3, -v3, vcc
	v_fmac_f32_e32 v3, v196, v19
	v_mov_b32_e32 v19, v3
.LBB0_440:
	s_or_b64 exec, exec, s[4:5]
	v_mov_b64_e32 v[34:35], s[34:35]
	v_mad_i64_i32 v[2:3], s[4:5], v2, s65, v[34:35]
	v_mul_f32_e32 v19, 0x3e16c740, v19
	v_cvt_pk_bf16_f32 v19, v19, s0
	v_lshl_add_u64 v[34:35], v[132:133], 1, v[2:3]
	global_store_short v[34:35], v19, off
	v_mul_f32_e32 v19, v37, v195
	s_and_saveexec_b64 s[4:5], s[42:43]
	s_cbranch_execz .LBB0_442
	ds_swizzle_b32 v20, v19 offset:swizzle(SWAP,16)
	s_waitcnt lgkmcnt(0)
	v_mul_f32_e32 v20, v197, v20
	v_cndmask_b32_e64 v20, v20, -v20, vcc
	v_fmac_f32_e32 v20, v196, v19
	v_mov_b32_e32 v19, v20
.LBB0_442:
	s_or_b64 exec, exec, s[4:5]
	v_mul_f32_e32 v19, 0x3e16c740, v19
	v_cvt_pk_bf16_f32 v19, v19, s0
	v_lshl_add_u64 v[2:3], v[136:137], 1, v[2:3]
	global_store_short v[2:3], v19, off offset:64
	v_mul_f32_e32 v19, v21, v195
	s_and_saveexec_b64 s[4:5], s[44:45]
	s_cbranch_execz .LBB0_444
	ds_swizzle_b32 v20, v19 offset:swizzle(SWAP,16)
	s_waitcnt lgkmcnt(0)
	v_mul_f32_e32 v20, v197, v20
	v_cndmask_b32_e64 v20, v20, -v20, vcc
	v_fmac_f32_e32 v20, v196, v19
	v_mov_b32_e32 v19, v20
.LBB0_444:
	s_or_b64 exec, exec, s[4:5]
	v_mul_f32_e32 v19, 0x3e16c740, v19
	v_cvt_pk_bf16_f32 v19, v19, s0
	v_mul_f32_e32 v0, v5, v195
	global_store_short v[2:3], v19, off offset:128
	s_and_saveexec_b64 s[4:5], s[46:47]
	s_cbranch_execz .LBB0_446
	ds_swizzle_b32 v5, v0 offset:swizzle(SWAP,16)
	s_waitcnt lgkmcnt(0)
	v_mul_f32_e32 v5, v197, v5
	v_cndmask_b32_e64 v5, v5, -v5, vcc
	v_fmac_f32_e32 v5, v196, v0
	v_mov_b32_e32 v0, v5
.LBB0_446:
	s_or_b64 exec, exec, s[4:5]
	v_mul_f32_e32 v0, 0x3e16c740, v0
	v_cvt_pk_bf16_f32 v0, v0, s0
	global_store_short v[2:3], v0, off offset:192
	v_or_b32_e32 v2, 40, v134
	v_ashrrev_i32_e32 v3, 31, v2
	v_lshl_add_u64 v[4:5], v[2:3], 2, s[28:29]
	global_load_dword v195, v[224:225], off offset:224
	global_load_dword v196, v[234:235], off offset:3072
	global_load_dword v197, v[234:235], off offset:3136
	v_add_u32_e32 v4, s13, v2
	v_ashrrev_i32_e32 v5, 31, v4
	v_lshlrev_b64 v[4:5], 7, v[4:5]
	v_lshl_add_u64 v[18:19], v[130:131], 0, v[4:5]
	s_waitcnt vmcnt(56)
	v_mul_f32_e32 v18, v54, v198
	s_and_saveexec_b64 s[4:5], s[40:41]
	s_cbranch_execz .LBB0_448
	ds_swizzle_b32 v3, v18 offset:swizzle(SWAP,16)
	s_waitcnt lgkmcnt(0)
	v_mul_f32_e32 v3, v200, v3
	v_cndmask_b32_e64 v3, v3, -v3, vcc
	v_fmac_f32_e32 v3, v199, v18
	v_mov_b32_e32 v18, v3
; __device__ __forceinline__ uint32_t pk2(float lo, float hi) { typedef float f2 __attribute__((ext_vector_type(2))); const f2 v = {lo, hi}; return __builtin_bit_cast(uint32_t, __builtin_convertvector(v, bf16x2_t)); }
; __device__ __forceinline__ void mla_up_tile(const Params& p, int b, int it, unsigned char* lds) {
;     ...
; #pragma unroll
;         for (int mi = 0; mi < 2; ++mi)
; #pragma unroll
;             for (int reg = 0; reg < 16; ++reg) {
;                 const int m = pm * 128 + wr * 64 + mi * 32 + (reg & 3) + 8 * (reg >> 2) + 4 * h;
;                 const float rq = RQ[m] ;
;                 const float* rp = rope + (size_t)(b * TH + m) * 32;
;                 const float cs = rp[r & 15], sn = rp[16 + (r & 15)];
; #pragma unroll
;                 for (int ni = 0; ni < 4; ++ni) {
;                     const int nb = pn * 256 + wc * 128 + ni * 32, n = nb + r;
;                     float v = acc[mi][ni][reg] * rq;
;                     if (((nb >> 5) % 3) == 2) {
;                         const float o = __builtin_bit_cast(float, __builtin_amdgcn_ds_swizzle(__builtin_bit_cast(int, v), 0x401f));
;                         v = (r < 16) ? (v * cs - o * sn) : (v * cs + o * sn);
;                     }
;                     QF[(size_t)m * 768 + n] = (bf16_t)(pk2(v * qsc, 0.f) & 0xffff);
;                 }
;             }
.LBB0_448:
	s_or_b64 exec, exec, s[4:5]
	v_mov_b64_e32 v[20:21], s[34:35]
	v_mad_i64_i32 v[2:3], s[4:5], v2, s65, v[20:21]
	v_mul_f32_e32 v18, 0x3e16c740, v18
	v_cvt_pk_bf16_f32 v20, v18, s0
	v_lshl_add_u64 v[18:19], v[132:133], 1, v[2:3]
	global_store_short v[18:19], v20, off
	v_mul_f32_e32 v18, v38, v198
	s_and_saveexec_b64 s[4:5], s[42:43]
	s_cbranch_execz .LBB0_450
	ds_swizzle_b32 v19, v18 offset:swizzle(SWAP,16)
	s_waitcnt lgkmcnt(0)
	v_mul_f32_e32 v19, v200, v19
	v_cndmask_b32_e64 v19, v19, -v19, vcc
	v_fmac_f32_e32 v19, v199, v18
	v_mov_b32_e32 v18, v19
.LBB0_450:
	s_or_b64 exec, exec, s[4:5]
	v_mul_f32_e32 v18, 0x3e16c740, v18
	v_cvt_pk_bf16_f32 v18, v18, s0
	v_lshl_add_u64 v[2:3], v[136:137], 1, v[2:3]
	global_store_short v[2:3], v18, off offset:64
	v_mul_f32_e32 v18, v22, v198
	s_and_saveexec_b64 s[4:5], s[44:45]
	s_cbranch_execz .LBB0_452
	ds_swizzle_b32 v19, v18 offset:swizzle(SWAP,16)
	s_waitcnt lgkmcnt(0)
	v_mul_f32_e32 v19, v200, v19
	v_cndmask_b32_e64 v19, v19, -v19, vcc
	v_fmac_f32_e32 v19, v199, v18
	v_mov_b32_e32 v18, v19
.LBB0_452:
	s_or_b64 exec, exec, s[4:5]
	v_mul_f32_e32 v18, 0x3e16c740, v18
	v_cvt_pk_bf16_f32 v18, v18, s0
	v_mul_f32_e32 v0, v6, v198
	global_store_short v[2:3], v18, off offset:128
	s_and_saveexec_b64 s[4:5], s[46:47]
	s_cbranch_execz .LBB0_454
	ds_swizzle_b32 v6, v0 offset:swizzle(SWAP,16)
	s_waitcnt lgkmcnt(0)
	v_mul_f32_e32 v5, v200, v6
	v_cndmask_b32_e64 v5, v5, -v5, vcc
	v_fmac_f32_e32 v5, v199, v0
	v_mov_b32_e32 v0, v5
.LBB0_454:
	s_or_b64 exec, exec, s[4:5]
	v_mul_f32_e32 v0, 0x3e16c740, v0
	v_cvt_pk_bf16_f32 v0, v0, s0
	global_store_short v[2:3], v0, off offset:192
	v_or_b32_e32 v2, 41, v134
	v_ashrrev_i32_e32 v3, 31, v2
	v_lshl_add_u64 v[4:5], v[2:3], 2, s[28:29]
	global_load_dword v198, v[224:225], off offset:228
	global_load_dword v199, v[234:235], off offset:3200
	global_load_dword v200, v[234:235], off offset:3264
	v_add_u32_e32 v4, s13, v2
	v_ashrrev_i32_e32 v5, 31, v4
	v_lshlrev_b64 v[4:5], 7, v[4:5]
	v_lshl_add_u64 v[18:19], v[130:131], 0, v[4:5]
	s_waitcnt vmcnt(56)
	v_mul_f32_e32 v6, v55, v201
	s_and_saveexec_b64 s[4:5], s[40:41]
	s_cbranch_execz .LBB0_456
	ds_swizzle_b32 v3, v6 offset:swizzle(SWAP,16)
	s_waitcnt lgkmcnt(0)
	v_mul_f32_e32 v3, v203, v3
	v_cndmask_b32_e64 v3, v3, -v3, vcc
	v_fmac_f32_e32 v3, v202, v6
	v_mov_b32_e32 v6, v3
.LBB0_456:
	s_or_b64 exec, exec, s[4:5]
	v_mov_b64_e32 v[18:19], s[34:35]
	v_mad_i64_i32 v[2:3], s[4:5], v2, s65, v[18:19]
	v_mul_f32_e32 v6, 0x3e16c740, v6
	v_cvt_pk_bf16_f32 v6, v6, s0
	v_lshl_add_u64 v[18:19], v[132:133], 1, v[2:3]
	global_store_short v[18:19], v6, off
	v_mul_f32_e32 v6, v39, v201
	s_and_saveexec_b64 s[4:5], s[42:43]
	s_cbranch_execz .LBB0_458
	ds_swizzle_b32 v18, v6 offset:swizzle(SWAP,16)
	s_waitcnt lgkmcnt(0)
	v_mul_f32_e32 v18, v203, v18
	v_cndmask_b32_e64 v18, v18, -v18, vcc
	v_fmac_f32_e32 v18, v202, v6
	v_mov_b32_e32 v6, v18
.LBB0_458:
	s_or_b64 exec, exec, s[4:5]
	v_mul_f32_e32 v6, 0x3e16c740, v6
	v_cvt_pk_bf16_f32 v6, v6, s0
	v_lshl_add_u64 v[2:3], v[136:137], 1, v[2:3]
	global_store_short v[2:3], v6, off offset:64
	v_mul_f32_e32 v6, v23, v201
	s_and_saveexec_b64 s[4:5], s[44:45]
	s_cbranch_execz .LBB0_460
	ds_swizzle_b32 v18, v6 offset:swizzle(SWAP,16)
	s_waitcnt lgkmcnt(0)
	v_mul_f32_e32 v18, v203, v18
	v_cndmask_b32_e64 v18, v18, -v18, vcc
	v_fmac_f32_e32 v18, v202, v6
	v_mov_b32_e32 v6, v18
.LBB0_460:
	s_or_b64 exec, exec, s[4:5]
	v_mul_f32_e32 v6, 0x3e16c740, v6
	v_cvt_pk_bf16_f32 v6, v6, s0
	v_mul_f32_e32 v0, v7, v201
	global_store_short v[2:3], v6, off offset:128
	s_and_saveexec_b64 s[4:5], s[46:47]
	s_cbranch_execz .LBB0_462
	ds_swizzle_b32 v6, v0 offset:swizzle(SWAP,16)
	s_waitcnt lgkmcnt(0)
	v_mul_f32_e32 v5, v203, v6
	v_cndmask_b32_e64 v5, v5, -v5, vcc
	v_fmac_f32_e32 v5, v202, v0
	v_mov_b32_e32 v0, v5
.LBB0_462:
	s_or_b64 exec, exec, s[4:5]
	v_mul_f32_e32 v0, 0x3e16c740, v0
	v_cvt_pk_bf16_f32 v0, v0, s0
	global_store_short v[2:3], v0, off offset:192
	v_or_b32_e32 v2, 42, v134
	v_ashrrev_i32_e32 v3, 31, v2
	v_lshl_add_u64 v[4:5], v[2:3], 2, s[28:29]
	global_load_dword v201, v[224:225], off offset:232
	global_load_dword v202, v[234:235], off offset:3328
	global_load_dword v203, v[234:235], off offset:3392
	v_add_u32_e32 v4, s13, v2
	v_ashrrev_i32_e32 v5, 31, v4
	v_lshlrev_b64 v[4:5], 7, v[4:5]
	v_lshl_add_u64 v[6:7], v[130:131], 0, v[4:5]
	s_waitcnt vmcnt(56)
	v_mul_f32_e32 v6, v56, v204
	s_and_saveexec_b64 s[4:5], s[40:41]
	s_cbranch_execz .LBB0_464
	ds_swizzle_b32 v3, v6 offset:swizzle(SWAP,16)
	s_waitcnt lgkmcnt(0)
	v_mul_f32_e32 v3, v206, v3
	v_cndmask_b32_e64 v3, v3, -v3, vcc
	v_fmac_f32_e32 v3, v205, v6
	v_mov_b32_e32 v6, v3
.LBB0_464:
	s_or_b64 exec, exec, s[4:5]
	v_mov_b64_e32 v[18:19], s[34:35]
	v_mad_i64_i32 v[2:3], s[4:5], v2, s65, v[18:19]
	v_mul_f32_e32 v6, 0x3e16c740, v6
	v_cvt_pk_bf16_f32 v18, v6, s0
	v_lshl_add_u64 v[6:7], v[132:133], 1, v[2:3]
	global_store_short v[6:7], v18, off
	v_mul_f32_e32 v6, v40, v204
	s_and_saveexec_b64 s[4:5], s[42:43]
	s_cbranch_execz .LBB0_466
	ds_swizzle_b32 v7, v6 offset:swizzle(SWAP,16)
	s_waitcnt lgkmcnt(0)
	v_mul_f32_e32 v7, v206, v7
	v_cndmask_b32_e64 v7, v7, -v7, vcc
	v_fmac_f32_e32 v7, v205, v6
	v_mov_b32_e32 v6, v7
.LBB0_466:
	s_or_b64 exec, exec, s[4:5]
	v_mul_f32_e32 v6, 0x3e16c740, v6
	v_cvt_pk_bf16_f32 v6, v6, s0
	v_lshl_add_u64 v[2:3], v[136:137], 1, v[2:3]
	global_store_short v[2:3], v6, off offset:64
	v_mul_f32_e32 v6, v24, v204
	s_and_saveexec_b64 s[4:5], s[44:45]
	s_cbranch_execz .LBB0_468
	ds_swizzle_b32 v7, v6 offset:swizzle(SWAP,16)
	s_waitcnt lgkmcnt(0)
	v_mul_f32_e32 v7, v206, v7
	v_cndmask_b32_e64 v7, v7, -v7, vcc
	v_fmac_f32_e32 v7, v205, v6
	v_mov_b32_e32 v6, v7
; __device__ __forceinline__ uint32_t pk2(float lo, float hi) { typedef float f2 __attribute__((ext_vector_type(2))); const f2 v = {lo, hi}; return __builtin_bit_cast(uint32_t, __builtin_convertvector(v, bf16x2_t)); }
; __device__ __forceinline__ void mla_up_tile(const Params& p, int b, int it, unsigned char* lds) {
;     ...
; #pragma unroll
;         for (int mi = 0; mi < 2; ++mi)
; #pragma unroll
;             for (int reg = 0; reg < 16; ++reg) {
;                 const int m = pm * 128 + wr * 64 + mi * 32 + (reg & 3) + 8 * (reg >> 2) + 4 * h;
;                 const float rq = RQ[m] ;
;                 const float* rp = rope + (size_t)(b * TH + m) * 32;
;                 const float cs = rp[r & 15], sn = rp[16 + (r & 15)];
; #pragma unroll
;                 for (int ni = 0; ni < 4; ++ni) {
;                     const int nb = pn * 256 + wc * 128 + ni * 32, n = nb + r;
;                     float v = acc[mi][ni][reg] * rq;
;                     if (((nb >> 5) % 3) == 2) {
;                         const float o = __builtin_bit_cast(float, __builtin_amdgcn_ds_swizzle(__builtin_bit_cast(int, v), 0x401f));
;                         v = (r < 16) ? (v * cs - o * sn) : (v * cs + o * sn);
;                     }
;                     QF[(size_t)m * 768 + n] = (bf16_t)(pk2(v * qsc, 0.f) & 0xffff);
;                 }
;             }
.LBB0_468:
	s_or_b64 exec, exec, s[4:5]
	v_mul_f32_e32 v6, 0x3e16c740, v6
	v_cvt_pk_bf16_f32 v6, v6, s0
	v_mul_f32_e32 v0, v8, v204
	global_store_short v[2:3], v6, off offset:128
	s_and_saveexec_b64 s[4:5], s[46:47]
	s_cbranch_execz .LBB0_470
	ds_swizzle_b32 v6, v0 offset:swizzle(SWAP,16)
	s_waitcnt lgkmcnt(0)
	v_mul_f32_e32 v5, v206, v6
	v_cndmask_b32_e64 v5, v5, -v5, vcc
	v_fmac_f32_e32 v5, v205, v0
	v_mov_b32_e32 v0, v5
.LBB0_470:
	s_or_b64 exec, exec, s[4:5]
	v_mul_f32_e32 v0, 0x3e16c740, v0
	v_cvt_pk_bf16_f32 v0, v0, s0
	global_store_short v[2:3], v0, off offset:192
	v_or_b32_e32 v2, 43, v134
	v_ashrrev_i32_e32 v3, 31, v2
	v_lshl_add_u64 v[4:5], v[2:3], 2, s[28:29]
	global_load_dword v204, v[224:225], off offset:236
	global_load_dword v205, v[234:235], off offset:3456
	global_load_dword v206, v[234:235], off offset:3520
	v_add_u32_e32 v4, s13, v2
	v_ashrrev_i32_e32 v5, 31, v4
	v_lshlrev_b64 v[4:5], 7, v[4:5]
	v_lshl_add_u64 v[6:7], v[130:131], 0, v[4:5]
	s_waitcnt vmcnt(56)
	v_mul_f32_e32 v6, v57, v207
	s_and_saveexec_b64 s[4:5], s[40:41]
	s_cbranch_execz .LBB0_472
	ds_swizzle_b32 v3, v6 offset:swizzle(SWAP,16)
	s_waitcnt lgkmcnt(0)
	v_mul_f32_e32 v3, v209, v3
	v_cndmask_b32_e64 v3, v3, -v3, vcc
	v_fmac_f32_e32 v3, v208, v6
	v_mov_b32_e32 v6, v3
.LBB0_472:
	s_or_b64 exec, exec, s[4:5]
	v_mov_b64_e32 v[18:19], s[34:35]
	v_mad_i64_i32 v[2:3], s[4:5], v2, s65, v[18:19]
	v_mul_f32_e32 v6, 0x3e16c740, v6
	v_cvt_pk_bf16_f32 v8, v6, s0
	v_lshl_add_u64 v[6:7], v[132:133], 1, v[2:3]
	global_store_short v[6:7], v8, off
	v_mul_f32_e32 v6, v41, v207
	s_and_saveexec_b64 s[4:5], s[42:43]
	s_cbranch_execz .LBB0_474
	ds_swizzle_b32 v7, v6 offset:swizzle(SWAP,16)
	s_waitcnt lgkmcnt(0)
	v_mul_f32_e32 v7, v209, v7
	v_cndmask_b32_e64 v7, v7, -v7, vcc
	v_fmac_f32_e32 v7, v208, v6
	v_mov_b32_e32 v6, v7
.LBB0_474:
	s_or_b64 exec, exec, s[4:5]
	v_mul_f32_e32 v6, 0x3e16c740, v6
	v_cvt_pk_bf16_f32 v6, v6, s0
	v_lshl_add_u64 v[2:3], v[136:137], 1, v[2:3]
	global_store_short v[2:3], v6, off offset:64
	v_mul_f32_e32 v6, v25, v207
	s_and_saveexec_b64 s[4:5], s[44:45]
	s_cbranch_execz .LBB0_476
	ds_swizzle_b32 v7, v6 offset:swizzle(SWAP,16)
	s_waitcnt lgkmcnt(0)
	v_mul_f32_e32 v7, v209, v7
	v_cndmask_b32_e64 v7, v7, -v7, vcc
	v_fmac_f32_e32 v7, v208, v6
	v_mov_b32_e32 v6, v7
.LBB0_476:
	s_or_b64 exec, exec, s[4:5]
	v_mul_f32_e32 v6, 0x3e16c740, v6
	v_cvt_pk_bf16_f32 v6, v6, s0
	v_mul_f32_e32 v0, v9, v207
	global_store_short v[2:3], v6, off offset:128
	s_and_saveexec_b64 s[4:5], s[46:47]
	s_cbranch_execz .LBB0_478
	ds_swizzle_b32 v6, v0 offset:swizzle(SWAP,16)
	s_waitcnt lgkmcnt(0)
	v_mul_f32_e32 v5, v209, v6
	v_cndmask_b32_e64 v5, v5, -v5, vcc
	v_fmac_f32_e32 v5, v208, v0
	v_mov_b32_e32 v0, v5
.LBB0_478:
	s_or_b64 exec, exec, s[4:5]
	v_mul_f32_e32 v0, 0x3e16c740, v0
	v_cvt_pk_bf16_f32 v0, v0, s0
	global_store_short v[2:3], v0, off offset:192
	v_or_b32_e32 v2, 48, v134
	v_ashrrev_i32_e32 v3, 31, v2
	v_lshl_add_u64 v[4:5], v[2:3], 2, s[28:29]
	v_add_u32_e32 v4, s13, v2
	v_ashrrev_i32_e32 v5, 31, v4
	v_lshlrev_b64 v[4:5], 7, v[4:5]
	v_lshl_add_u64 v[6:7], v[130:131], 0, v[4:5]
	s_waitcnt vmcnt(53)
	v_mul_f32_e32 v6, v58, v210
	s_and_saveexec_b64 s[4:5], s[40:41]
	s_cbranch_execz .LBB0_480
	ds_swizzle_b32 v3, v6 offset:swizzle(SWAP,16)
	s_waitcnt lgkmcnt(0)
	v_mul_f32_e32 v3, v212, v3
	v_cndmask_b32_e64 v3, v3, -v3, vcc
	v_fmac_f32_e32 v3, v211, v6
	v_mov_b32_e32 v6, v3
.LBB0_480:
	s_or_b64 exec, exec, s[4:5]
	v_mov_b64_e32 v[8:9], s[34:35]
	v_mad_i64_i32 v[2:3], s[4:5], v2, s65, v[8:9]
	v_mul_f32_e32 v6, 0x3e16c740, v6
	v_cvt_pk_bf16_f32 v8, v6, s0
	v_lshl_add_u64 v[6:7], v[132:133], 1, v[2:3]
	global_store_short v[6:7], v8, off
	v_mul_f32_e32 v6, v42, v210
	s_and_saveexec_b64 s[4:5], s[42:43]
	s_cbranch_execz .LBB0_482
	ds_swizzle_b32 v7, v6 offset:swizzle(SWAP,16)
	s_waitcnt lgkmcnt(0)
	v_mul_f32_e32 v7, v212, v7
	v_cndmask_b32_e64 v7, v7, -v7, vcc
	v_fmac_f32_e32 v7, v211, v6
	v_mov_b32_e32 v6, v7
.LBB0_482:
	s_or_b64 exec, exec, s[4:5]
	v_mul_f32_e32 v6, 0x3e16c740, v6
	v_cvt_pk_bf16_f32 v6, v6, s0
	v_lshl_add_u64 v[2:3], v[136:137], 1, v[2:3]
	global_store_short v[2:3], v6, off offset:64
	v_mul_f32_e32 v6, v26, v210
	s_and_saveexec_b64 s[4:5], s[44:45]
	s_cbranch_execz .LBB0_484
	ds_swizzle_b32 v7, v6 offset:swizzle(SWAP,16)
	s_waitcnt lgkmcnt(0)
	v_mul_f32_e32 v7, v212, v7
	v_cndmask_b32_e64 v7, v7, -v7, vcc
	v_fmac_f32_e32 v7, v211, v6
	v_mov_b32_e32 v6, v7
.LBB0_484:
	s_or_b64 exec, exec, s[4:5]
	v_mul_f32_e32 v6, 0x3e16c740, v6
	v_cvt_pk_bf16_f32 v6, v6, s0
	v_mul_f32_e32 v0, v10, v210
	global_store_short v[2:3], v6, off offset:128
	s_and_saveexec_b64 s[4:5], s[46:47]
	s_cbranch_execz .LBB0_486
	ds_swizzle_b32 v6, v0 offset:swizzle(SWAP,16)
	s_waitcnt lgkmcnt(0)
	v_mul_f32_e32 v5, v212, v6
	v_cndmask_b32_e64 v5, v5, -v5, vcc
	v_fmac_f32_e32 v5, v211, v0
	v_mov_b32_e32 v0, v5
.LBB0_486:
	s_or_b64 exec, exec, s[4:5]
	v_mul_f32_e32 v0, 0x3e16c740, v0
	v_cvt_pk_bf16_f32 v0, v0, s0
	global_store_short v[2:3], v0, off offset:192
	v_or_b32_e32 v2, 49, v134
	v_ashrrev_i32_e32 v3, 31, v2
	v_lshl_add_u64 v[4:5], v[2:3], 2, s[28:29]
	v_add_u32_e32 v4, s13, v2
	v_ashrrev_i32_e32 v5, 31, v4
	v_lshlrev_b64 v[4:5], 7, v[4:5]
	v_lshl_add_u64 v[6:7], v[130:131], 0, v[4:5]
	s_waitcnt vmcnt(50)
	v_mul_f32_e32 v6, v59, v213
	s_and_saveexec_b64 s[4:5], s[40:41]
	s_cbranch_execz .LBB0_488
	ds_swizzle_b32 v3, v6 offset:swizzle(SWAP,16)
	s_waitcnt lgkmcnt(0)
	v_mul_f32_e32 v3, v215, v3
	v_cndmask_b32_e64 v3, v3, -v3, vcc
	v_fmac_f32_e32 v3, v214, v6
	v_mov_b32_e32 v6, v3
; __device__ __forceinline__ uint32_t pk2(float lo, float hi) { typedef float f2 __attribute__((ext_vector_type(2))); const f2 v = {lo, hi}; return __builtin_bit_cast(uint32_t, __builtin_convertvector(v, bf16x2_t)); }
; __device__ __forceinline__ void mla_up_tile(const Params& p, int b, int it, unsigned char* lds) {
;     ...
; #pragma unroll
;         for (int mi = 0; mi < 2; ++mi)
; #pragma unroll
;             for (int reg = 0; reg < 16; ++reg) {
;                 const int m = pm * 128 + wr * 64 + mi * 32 + (reg & 3) + 8 * (reg >> 2) + 4 * h;
;                 const float rq = RQ[m] ;
;                 const float* rp = rope + (size_t)(b * TH + m) * 32;
;                 const float cs = rp[r & 15], sn = rp[16 + (r & 15)];
; #pragma unroll
;                 for (int ni = 0; ni < 4; ++ni) {
;                     const int nb = pn * 256 + wc * 128 + ni * 32, n = nb + r;
;                     float v = acc[mi][ni][reg] * rq;
;                     if (((nb >> 5) % 3) == 2) {
;                         const float o = __builtin_bit_cast(float, __builtin_amdgcn_ds_swizzle(__builtin_bit_cast(int, v), 0x401f));
;                         v = (r < 16) ? (v * cs - o * sn) : (v * cs + o * sn);
;                     }
;                     QF[(size_t)m * 768 + n] = (bf16_t)(pk2(v * qsc, 0.f) & 0xffff);
;                 }
;             }
.LBB0_488:
	s_or_b64 exec, exec, s[4:5]
	v_mov_b64_e32 v[8:9], s[34:35]
	v_mad_i64_i32 v[2:3], s[4:5], v2, s65, v[8:9]
	v_mul_f32_e32 v6, 0x3e16c740, v6
	v_cvt_pk_bf16_f32 v8, v6, s0
	v_lshl_add_u64 v[6:7], v[132:133], 1, v[2:3]
	global_store_short v[6:7], v8, off
	v_mul_f32_e32 v6, v43, v213
	s_and_saveexec_b64 s[4:5], s[42:43]
	s_cbranch_execz .LBB0_490
	ds_swizzle_b32 v7, v6 offset:swizzle(SWAP,16)
	s_waitcnt lgkmcnt(0)
	v_mul_f32_e32 v7, v215, v7
	v_cndmask_b32_e64 v7, v7, -v7, vcc
	v_fmac_f32_e32 v7, v214, v6
	v_mov_b32_e32 v6, v7
.LBB0_490:
	s_or_b64 exec, exec, s[4:5]
	v_mul_f32_e32 v6, 0x3e16c740, v6
	v_cvt_pk_bf16_f32 v6, v6, s0
	v_lshl_add_u64 v[2:3], v[136:137], 1, v[2:3]
	global_store_short v[2:3], v6, off offset:64
	v_mul_f32_e32 v6, v27, v213
	s_and_saveexec_b64 s[4:5], s[44:45]
	s_cbranch_execz .LBB0_492
	ds_swizzle_b32 v7, v6 offset:swizzle(SWAP,16)
	s_waitcnt lgkmcnt(0)
	v_mul_f32_e32 v7, v215, v7
	v_cndmask_b32_e64 v7, v7, -v7, vcc
	v_fmac_f32_e32 v7, v214, v6
	v_mov_b32_e32 v6, v7
.LBB0_492:
	s_or_b64 exec, exec, s[4:5]
	v_mul_f32_e32 v6, 0x3e16c740, v6
	v_cvt_pk_bf16_f32 v6, v6, s0
	v_mul_f32_e32 v0, v11, v213
	global_store_short v[2:3], v6, off offset:128
	s_and_saveexec_b64 s[4:5], s[46:47]
	s_cbranch_execz .LBB0_494
	ds_swizzle_b32 v6, v0 offset:swizzle(SWAP,16)
	s_waitcnt lgkmcnt(0)
	v_mul_f32_e32 v5, v215, v6
	v_cndmask_b32_e64 v5, v5, -v5, vcc
	v_fmac_f32_e32 v5, v214, v0
	v_mov_b32_e32 v0, v5
.LBB0_494:
	s_or_b64 exec, exec, s[4:5]
	v_mul_f32_e32 v0, 0x3e16c740, v0
	v_cvt_pk_bf16_f32 v0, v0, s0
	global_store_short v[2:3], v0, off offset:192
	v_or_b32_e32 v2, 50, v134
	v_ashrrev_i32_e32 v3, 31, v2
	v_lshl_add_u64 v[4:5], v[2:3], 2, s[28:29]
	v_add_u32_e32 v4, s13, v2
	v_ashrrev_i32_e32 v5, 31, v4
	v_lshlrev_b64 v[4:5], 7, v[4:5]
	v_lshl_add_u64 v[6:7], v[130:131], 0, v[4:5]
	s_waitcnt vmcnt(47)
	v_mul_f32_e32 v6, v60, v216
	s_and_saveexec_b64 s[4:5], s[40:41]
	s_cbranch_execz .LBB0_496
	ds_swizzle_b32 v3, v6 offset:swizzle(SWAP,16)
	s_waitcnt lgkmcnt(0)
	v_mul_f32_e32 v3, v218, v3
	v_cndmask_b32_e64 v3, v3, -v3, vcc
	v_fmac_f32_e32 v3, v217, v6
	v_mov_b32_e32 v6, v3
.LBB0_496:
	s_or_b64 exec, exec, s[4:5]
	v_mov_b64_e32 v[8:9], s[34:35]
	v_mad_i64_i32 v[2:3], s[4:5], v2, s65, v[8:9]
	v_mul_f32_e32 v6, 0x3e16c740, v6
	v_cvt_pk_bf16_f32 v8, v6, s0
	v_lshl_add_u64 v[6:7], v[132:133], 1, v[2:3]
	global_store_short v[6:7], v8, off
	v_mul_f32_e32 v6, v44, v216
	s_and_saveexec_b64 s[4:5], s[42:43]
	s_cbranch_execz .LBB0_498
	ds_swizzle_b32 v7, v6 offset:swizzle(SWAP,16)
	s_waitcnt lgkmcnt(0)
	v_mul_f32_e32 v7, v218, v7
	v_cndmask_b32_e64 v7, v7, -v7, vcc
	v_fmac_f32_e32 v7, v217, v6
	v_mov_b32_e32 v6, v7
.LBB0_498:
	s_or_b64 exec, exec, s[4:5]
	v_mul_f32_e32 v6, 0x3e16c740, v6
	v_cvt_pk_bf16_f32 v6, v6, s0
	v_lshl_add_u64 v[2:3], v[136:137], 1, v[2:3]
	global_store_short v[2:3], v6, off offset:64
	v_mul_f32_e32 v6, v28, v216
	s_and_saveexec_b64 s[4:5], s[44:45]
	s_cbranch_execz .LBB0_500
	ds_swizzle_b32 v7, v6 offset:swizzle(SWAP,16)
	s_waitcnt lgkmcnt(0)
	v_mul_f32_e32 v7, v218, v7
	v_cndmask_b32_e64 v7, v7, -v7, vcc
	v_fmac_f32_e32 v7, v217, v6
	v_mov_b32_e32 v6, v7
.LBB0_500:
	s_or_b64 exec, exec, s[4:5]
	v_mul_f32_e32 v6, 0x3e16c740, v6
	v_cvt_pk_bf16_f32 v6, v6, s0
	v_mul_f32_e32 v0, v12, v216
	global_store_short v[2:3], v6, off offset:128
	s_and_saveexec_b64 s[4:5], s[46:47]
	s_cbranch_execz .LBB0_502
	ds_swizzle_b32 v6, v0 offset:swizzle(SWAP,16)
	s_waitcnt lgkmcnt(0)
	v_mul_f32_e32 v5, v218, v6
	v_cndmask_b32_e64 v5, v5, -v5, vcc
	v_fmac_f32_e32 v5, v217, v0
	v_mov_b32_e32 v0, v5
.LBB0_502:
	s_or_b64 exec, exec, s[4:5]
	v_mul_f32_e32 v0, 0x3e16c740, v0
	v_cvt_pk_bf16_f32 v0, v0, s0
	global_store_short v[2:3], v0, off offset:192
	v_or_b32_e32 v2, 51, v134
	v_ashrrev_i32_e32 v3, 31, v2
	v_lshl_add_u64 v[4:5], v[2:3], 2, s[28:29]
	v_add_u32_e32 v4, s13, v2
	v_ashrrev_i32_e32 v5, 31, v4
	v_lshlrev_b64 v[4:5], 7, v[4:5]
	v_lshl_add_u64 v[6:7], v[130:131], 0, v[4:5]
	s_waitcnt vmcnt(44)
	v_mul_f32_e32 v6, v61, v192
	s_and_saveexec_b64 s[4:5], s[40:41]
	s_cbranch_execz .LBB0_504
	ds_swizzle_b32 v3, v6 offset:swizzle(SWAP,16)
	s_waitcnt lgkmcnt(0)
	v_mul_f32_e32 v3, v194, v3
	v_cndmask_b32_e64 v3, v3, -v3, vcc
	v_fmac_f32_e32 v3, v193, v6
	v_mov_b32_e32 v6, v3
.LBB0_504:
	s_or_b64 exec, exec, s[4:5]
	v_mov_b64_e32 v[8:9], s[34:35]
	v_mad_i64_i32 v[2:3], s[4:5], v2, s65, v[8:9]
	v_mul_f32_e32 v6, 0x3e16c740, v6
	v_cvt_pk_bf16_f32 v8, v6, s0
	v_lshl_add_u64 v[6:7], v[132:133], 1, v[2:3]
	global_store_short v[6:7], v8, off
	v_mul_f32_e32 v6, v45, v192
	s_and_saveexec_b64 s[4:5], s[42:43]
	s_cbranch_execz .LBB0_506
	ds_swizzle_b32 v7, v6 offset:swizzle(SWAP,16)
	s_waitcnt lgkmcnt(0)
	v_mul_f32_e32 v7, v194, v7
	v_cndmask_b32_e64 v7, v7, -v7, vcc
	v_fmac_f32_e32 v7, v193, v6
	v_mov_b32_e32 v6, v7
.LBB0_506:
	s_or_b64 exec, exec, s[4:5]
	v_mul_f32_e32 v6, 0x3e16c740, v6
	v_cvt_pk_bf16_f32 v6, v6, s0
	v_lshl_add_u64 v[2:3], v[136:137], 1, v[2:3]
	global_store_short v[2:3], v6, off offset:64
	v_mul_f32_e32 v6, v29, v192
	s_and_saveexec_b64 s[4:5], s[44:45]
	s_cbranch_execz .LBB0_508
	ds_swizzle_b32 v7, v6 offset:swizzle(SWAP,16)
	s_waitcnt lgkmcnt(0)
	v_mul_f32_e32 v7, v194, v7
	v_cndmask_b32_e64 v7, v7, -v7, vcc
	v_fmac_f32_e32 v7, v193, v6
	v_mov_b32_e32 v6, v7
.LBB0_508:
	s_or_b64 exec, exec, s[4:5]
	v_mul_f32_e32 v6, 0x3e16c740, v6
	v_cvt_pk_bf16_f32 v6, v6, s0
	v_mul_f32_e32 v0, v13, v192
	global_store_short v[2:3], v6, off offset:128
	s_and_saveexec_b64 s[4:5], s[46:47]
	s_cbranch_execz .LBB0_510
	ds_swizzle_b32 v6, v0 offset:swizzle(SWAP,16)
	s_waitcnt lgkmcnt(0)
	v_mul_f32_e32 v5, v194, v6
	v_cndmask_b32_e64 v5, v5, -v5, vcc
	v_fmac_f32_e32 v5, v193, v0
	v_mov_b32_e32 v0, v5
; __device__ __forceinline__ uint32_t pk2(float lo, float hi) { typedef float f2 __attribute__((ext_vector_type(2))); const f2 v = {lo, hi}; return __builtin_bit_cast(uint32_t, __builtin_convertvector(v, bf16x2_t)); }
; __device__ __forceinline__ void mla_up_tile(const Params& p, int b, int it, unsigned char* lds) {
;     ...
; #pragma unroll
;         for (int mi = 0; mi < 2; ++mi)
; #pragma unroll
;             for (int reg = 0; reg < 16; ++reg) {
;                 const int m = pm * 128 + wr * 64 + mi * 32 + (reg & 3) + 8 * (reg >> 2) + 4 * h;
;                 const float rq = RQ[m] ;
;                 const float* rp = rope + (size_t)(b * TH + m) * 32;
;                 const float cs = rp[r & 15], sn = rp[16 + (r & 15)];
; #pragma unroll
;                 for (int ni = 0; ni < 4; ++ni) {
;                     const int nb = pn * 256 + wc * 128 + ni * 32, n = nb + r;
;                     float v = acc[mi][ni][reg] * rq;
;                     if (((nb >> 5) % 3) == 2) {
;                         const float o = __builtin_bit_cast(float, __builtin_amdgcn_ds_swizzle(__builtin_bit_cast(int, v), 0x401f));
;                         v = (r < 16) ? (v * cs - o * sn) : (v * cs + o * sn);
;                     }
;                     QF[(size_t)m * 768 + n] = (bf16_t)(pk2(v * qsc, 0.f) & 0xffff);
;                 }
;             }
.LBB0_510:
	s_or_b64 exec, exec, s[4:5]
	v_mul_f32_e32 v0, 0x3e16c740, v0
	v_cvt_pk_bf16_f32 v0, v0, s0
	global_store_short v[2:3], v0, off offset:192
	v_or_b32_e32 v2, 56, v134
	v_ashrrev_i32_e32 v3, 31, v2
	v_lshl_add_u64 v[4:5], v[2:3], 2, s[28:29]
	v_add_u32_e32 v4, s13, v2
	v_ashrrev_i32_e32 v5, 31, v4
	v_lshlrev_b64 v[4:5], 7, v[4:5]
	v_lshl_add_u64 v[6:7], v[130:131], 0, v[4:5]
	s_waitcnt vmcnt(41)
	v_mul_f32_e32 v6, v62, v195
	s_and_saveexec_b64 s[4:5], s[40:41]
	s_cbranch_execz .LBB0_512
	ds_swizzle_b32 v3, v6 offset:swizzle(SWAP,16)
	s_waitcnt lgkmcnt(0)
	v_mul_f32_e32 v3, v197, v3
	v_cndmask_b32_e64 v3, v3, -v3, vcc
	v_fmac_f32_e32 v3, v196, v6
	v_mov_b32_e32 v6, v3
.LBB0_512:
	s_or_b64 exec, exec, s[4:5]
	v_mov_b64_e32 v[8:9], s[34:35]
	v_mad_i64_i32 v[2:3], s[4:5], v2, s65, v[8:9]
	v_mul_f32_e32 v6, 0x3e16c740, v6
	v_cvt_pk_bf16_f32 v8, v6, s0
	v_lshl_add_u64 v[6:7], v[132:133], 1, v[2:3]
	global_store_short v[6:7], v8, off
	v_mul_f32_e32 v6, v46, v195
	s_and_saveexec_b64 s[4:5], s[42:43]
	s_cbranch_execz .LBB0_514
	ds_swizzle_b32 v7, v6 offset:swizzle(SWAP,16)
	s_waitcnt lgkmcnt(0)
	v_mul_f32_e32 v7, v197, v7
	v_cndmask_b32_e64 v7, v7, -v7, vcc
	v_fmac_f32_e32 v7, v196, v6
	v_mov_b32_e32 v6, v7
.LBB0_514:
	s_or_b64 exec, exec, s[4:5]
	v_mul_f32_e32 v6, 0x3e16c740, v6
	v_cvt_pk_bf16_f32 v6, v6, s0
	v_lshl_add_u64 v[2:3], v[136:137], 1, v[2:3]
	global_store_short v[2:3], v6, off offset:64
	v_mul_f32_e32 v6, v30, v195
	s_and_saveexec_b64 s[4:5], s[44:45]
	s_cbranch_execz .LBB0_516
	ds_swizzle_b32 v7, v6 offset:swizzle(SWAP,16)
	s_waitcnt lgkmcnt(0)
	v_mul_f32_e32 v7, v197, v7
	v_cndmask_b32_e64 v7, v7, -v7, vcc
	v_fmac_f32_e32 v7, v196, v6
	v_mov_b32_e32 v6, v7
.LBB0_516:
	s_or_b64 exec, exec, s[4:5]
	v_mul_f32_e32 v6, 0x3e16c740, v6
	v_cvt_pk_bf16_f32 v6, v6, s0
	v_mul_f32_e32 v0, v14, v195
	global_store_short v[2:3], v6, off offset:128
	s_and_saveexec_b64 s[4:5], s[46:47]
	s_cbranch_execz .LBB0_518
	ds_swizzle_b32 v6, v0 offset:swizzle(SWAP,16)
	s_waitcnt lgkmcnt(0)
	v_mul_f32_e32 v5, v197, v6
	v_cndmask_b32_e64 v5, v5, -v5, vcc
	v_fmac_f32_e32 v5, v196, v0
	v_mov_b32_e32 v0, v5
.LBB0_518:
	s_or_b64 exec, exec, s[4:5]
	v_mul_f32_e32 v0, 0x3e16c740, v0
	v_cvt_pk_bf16_f32 v0, v0, s0
	global_store_short v[2:3], v0, off offset:192
	v_or_b32_e32 v2, 57, v134
	v_ashrrev_i32_e32 v3, 31, v2
	v_lshl_add_u64 v[4:5], v[2:3], 2, s[28:29]
	v_add_u32_e32 v4, s13, v2
	v_ashrrev_i32_e32 v5, 31, v4
	v_lshlrev_b64 v[4:5], 7, v[4:5]
	v_lshl_add_u64 v[6:7], v[130:131], 0, v[4:5]
	s_waitcnt vmcnt(38)
	v_mul_f32_e32 v6, v63, v198
	s_and_saveexec_b64 s[4:5], s[40:41]
	s_cbranch_execz .LBB0_520
	ds_swizzle_b32 v3, v6 offset:swizzle(SWAP,16)
	s_waitcnt lgkmcnt(0)
	v_mul_f32_e32 v3, v200, v3
	v_cndmask_b32_e64 v3, v3, -v3, vcc
	v_fmac_f32_e32 v3, v199, v6
	v_mov_b32_e32 v6, v3
.LBB0_520:
	s_or_b64 exec, exec, s[4:5]
	v_mov_b64_e32 v[8:9], s[34:35]
	v_mad_i64_i32 v[2:3], s[4:5], v2, s65, v[8:9]
	v_mul_f32_e32 v6, 0x3e16c740, v6
	v_cvt_pk_bf16_f32 v8, v6, s0
	v_lshl_add_u64 v[6:7], v[132:133], 1, v[2:3]
	global_store_short v[6:7], v8, off
	v_mul_f32_e32 v6, v47, v198
	s_and_saveexec_b64 s[4:5], s[42:43]
	s_cbranch_execz .LBB0_522
	ds_swizzle_b32 v7, v6 offset:swizzle(SWAP,16)
	s_waitcnt lgkmcnt(0)
	v_mul_f32_e32 v7, v200, v7
	v_cndmask_b32_e64 v7, v7, -v7, vcc
	v_fmac_f32_e32 v7, v199, v6
	v_mov_b32_e32 v6, v7
.LBB0_522:
	s_or_b64 exec, exec, s[4:5]
	v_mul_f32_e32 v6, 0x3e16c740, v6
	v_cvt_pk_bf16_f32 v6, v6, s0
	v_lshl_add_u64 v[2:3], v[136:137], 1, v[2:3]
	global_store_short v[2:3], v6, off offset:64
	v_mul_f32_e32 v6, v31, v198
	s_and_saveexec_b64 s[4:5], s[44:45]
	s_cbranch_execz .LBB0_524
	ds_swizzle_b32 v7, v6 offset:swizzle(SWAP,16)
	s_waitcnt lgkmcnt(0)
	v_mul_f32_e32 v7, v200, v7
	v_cndmask_b32_e64 v7, v7, -v7, vcc
	v_fmac_f32_e32 v7, v199, v6
	v_mov_b32_e32 v6, v7
.LBB0_524:
	s_or_b64 exec, exec, s[4:5]
	v_mul_f32_e32 v6, 0x3e16c740, v6
	v_cvt_pk_bf16_f32 v6, v6, s0
	v_mul_f32_e32 v0, v15, v198
	global_store_short v[2:3], v6, off offset:128
	s_and_saveexec_b64 s[4:5], s[46:47]
	s_cbranch_execz .LBB0_526
	ds_swizzle_b32 v6, v0 offset:swizzle(SWAP,16)
	s_waitcnt lgkmcnt(0)
	v_mul_f32_e32 v5, v200, v6
	v_cndmask_b32_e64 v5, v5, -v5, vcc
	v_fmac_f32_e32 v5, v199, v0
	v_mov_b32_e32 v0, v5
; __device__ __forceinline__ uint32_t pk2(float lo, float hi) { typedef float f2 __attribute__((ext_vector_type(2))); const f2 v = {lo, hi}; return __builtin_bit_cast(uint32_t, __builtin_convertvector(v, bf16x2_t)); }
; __device__ __forceinline__ void mla_up_tile(const Params& p, int b, int it, unsigned char* lds) {
;     ...
; #pragma unroll
;         for (int mi = 0; mi < 2; ++mi)
; #pragma unroll
;             for (int reg = 0; reg < 16; ++reg) {
;                 const int m = pm * 128 + wr * 64 + mi * 32 + (reg & 3) + 8 * (reg >> 2) + 4 * h;
;                 const float rq = RQ[m] ;
;                 const float* rp = rope + (size_t)(b * TH + m) * 32;
;                 const float cs = rp[r & 15], sn = rp[16 + (r & 15)];
; #pragma unroll
;                 for (int ni = 0; ni < 4; ++ni) {
;                     const int nb = pn * 256 + wc * 128 + ni * 32, n = nb + r;
;                     float v = acc[mi][ni][reg] * rq;
;                     if (((nb >> 5) % 3) == 2) {
;                         const float o = __builtin_bit_cast(float, __builtin_amdgcn_ds_swizzle(__builtin_bit_cast(int, v), 0x401f));
;                         v = (r < 16) ? (v * cs - o * sn) : (v * cs + o * sn);
;                     }
;                     QF[(size_t)m * 768 + n] = (bf16_t)(pk2(v * qsc, 0.f) & 0xffff);
;                 }
;             }
.LBB0_526:
	s_or_b64 exec, exec, s[4:5]
	v_mul_f32_e32 v0, 0x3e16c740, v0
	v_cvt_pk_bf16_f32 v0, v0, s0
	global_store_short v[2:3], v0, off offset:192
	v_or_b32_e32 v2, 58, v134
	v_ashrrev_i32_e32 v3, 31, v2
	v_lshl_add_u64 v[4:5], v[2:3], 2, s[28:29]
	v_add_u32_e32 v4, s13, v2
	v_ashrrev_i32_e32 v5, 31, v4
	v_lshlrev_b64 v[4:5], 7, v[4:5]
	v_lshl_add_u64 v[6:7], v[130:131], 0, v[4:5]
	s_waitcnt vmcnt(35)
	v_mul_f32_e32 v6, v64, v201
	s_and_saveexec_b64 s[4:5], s[40:41]
	s_cbranch_execz .LBB0_528
	ds_swizzle_b32 v3, v6 offset:swizzle(SWAP,16)
	s_waitcnt lgkmcnt(0)
	v_mul_f32_e32 v3, v203, v3
	v_cndmask_b32_e64 v3, v3, -v3, vcc
	v_fmac_f32_e32 v3, v202, v6
	v_mov_b32_e32 v6, v3
.LBB0_528:
	s_or_b64 exec, exec, s[4:5]
	v_mov_b64_e32 v[8:9], s[34:35]
	v_mad_i64_i32 v[2:3], s[4:5], v2, s65, v[8:9]
	v_mul_f32_e32 v6, 0x3e16c740, v6
	v_cvt_pk_bf16_f32 v8, v6, s0
	v_lshl_add_u64 v[6:7], v[132:133], 1, v[2:3]
	global_store_short v[6:7], v8, off
	v_mul_f32_e32 v6, v48, v201
	s_and_saveexec_b64 s[4:5], s[42:43]
	s_cbranch_execz .LBB0_530
	ds_swizzle_b32 v7, v6 offset:swizzle(SWAP,16)
	s_waitcnt lgkmcnt(0)
	v_mul_f32_e32 v7, v203, v7
	v_cndmask_b32_e64 v7, v7, -v7, vcc
	v_fmac_f32_e32 v7, v202, v6
	v_mov_b32_e32 v6, v7
.LBB0_530:
	s_or_b64 exec, exec, s[4:5]
	v_mul_f32_e32 v6, 0x3e16c740, v6
	v_cvt_pk_bf16_f32 v6, v6, s0
	v_lshl_add_u64 v[2:3], v[136:137], 1, v[2:3]
	global_store_short v[2:3], v6, off offset:64
	v_mul_f32_e32 v6, v32, v201
	s_and_saveexec_b64 s[4:5], s[44:45]
	s_cbranch_execz .LBB0_532
	ds_swizzle_b32 v7, v6 offset:swizzle(SWAP,16)
	s_waitcnt lgkmcnt(0)
	v_mul_f32_e32 v7, v203, v7
	v_cndmask_b32_e64 v7, v7, -v7, vcc
	v_fmac_f32_e32 v7, v202, v6
	v_mov_b32_e32 v6, v7
.LBB0_532:
	s_or_b64 exec, exec, s[4:5]
	v_mul_f32_e32 v6, 0x3e16c740, v6
	v_cvt_pk_bf16_f32 v6, v6, s0
	v_mul_f32_e32 v0, v16, v201
	global_store_short v[2:3], v6, off offset:128
	s_and_saveexec_b64 s[4:5], s[46:47]
	s_cbranch_execz .LBB0_534
	ds_swizzle_b32 v6, v0 offset:swizzle(SWAP,16)
	s_waitcnt lgkmcnt(0)
	v_mul_f32_e32 v5, v203, v6
	v_cndmask_b32_e64 v5, v5, -v5, vcc
	v_fmac_f32_e32 v5, v202, v0
	v_mov_b32_e32 v0, v5
.LBB0_534:
	s_or_b64 exec, exec, s[4:5]
	v_mul_f32_e32 v0, 0x3e16c740, v0
	v_cvt_pk_bf16_f32 v0, v0, s0
	global_store_short v[2:3], v0, off offset:192
	v_or_b32_e32 v2, 59, v134
	v_ashrrev_i32_e32 v3, 31, v2
	v_lshl_add_u64 v[4:5], v[2:3], 2, s[28:29]
	v_add_u32_e32 v4, s13, v2
	v_ashrrev_i32_e32 v5, 31, v4
	v_lshlrev_b64 v[4:5], 7, v[4:5]
	v_lshl_add_u64 v[6:7], v[130:131], 0, v[4:5]
	s_waitcnt vmcnt(32)
	v_mul_f32_e32 v6, v65, v204
	s_and_saveexec_b64 s[4:5], s[40:41]
	s_cbranch_execz .LBB0_536
	ds_swizzle_b32 v3, v6 offset:swizzle(SWAP,16)
	s_waitcnt lgkmcnt(0)
	v_mul_f32_e32 v3, v206, v3
	v_cndmask_b32_e64 v3, v3, -v3, vcc
	v_fmac_f32_e32 v3, v205, v6
	v_mov_b32_e32 v6, v3
.LBB0_536:
	s_or_b64 exec, exec, s[4:5]
	v_mov_b64_e32 v[8:9], s[34:35]
	v_mad_i64_i32 v[2:3], s[4:5], v2, s65, v[8:9]
	v_mul_f32_e32 v6, 0x3e16c740, v6
	v_cvt_pk_bf16_f32 v8, v6, s0
	v_lshl_add_u64 v[6:7], v[132:133], 1, v[2:3]
	global_store_short v[6:7], v8, off
	v_mul_f32_e32 v6, v49, v204
	s_and_saveexec_b64 s[4:5], s[42:43]
	s_cbranch_execz .LBB0_538
	ds_swizzle_b32 v7, v6 offset:swizzle(SWAP,16)
	s_waitcnt lgkmcnt(0)
	v_mul_f32_e32 v7, v206, v7
	v_cndmask_b32_e64 v7, v7, -v7, vcc
	v_fmac_f32_e32 v7, v205, v6
	v_mov_b32_e32 v6, v7
.LBB0_538:
	s_or_b64 exec, exec, s[4:5]
	v_mul_f32_e32 v6, 0x3e16c740, v6
	v_cvt_pk_bf16_f32 v6, v6, s0
	v_lshl_add_u64 v[2:3], v[136:137], 1, v[2:3]
	global_store_short v[2:3], v6, off offset:64
	v_mul_f32_e32 v6, v33, v204
	s_and_saveexec_b64 s[4:5], s[44:45]
	s_cbranch_execz .LBB0_540
	ds_swizzle_b32 v7, v6 offset:swizzle(SWAP,16)
	s_waitcnt lgkmcnt(0)
	v_mul_f32_e32 v7, v206, v7
	v_cndmask_b32_e64 v7, v7, -v7, vcc
	v_fmac_f32_e32 v7, v205, v6
	v_mov_b32_e32 v6, v7
.LBB0_540:
	s_or_b64 exec, exec, s[4:5]
	v_mul_f32_e32 v6, 0x3e16c740, v6
	v_cvt_pk_bf16_f32 v6, v6, s0
	v_mul_f32_e32 v0, v17, v204
	global_store_short v[2:3], v6, off offset:128
	s_and_saveexec_b64 s[4:5], s[46:47]
	s_cbranch_execz .LBB0_271
	ds_swizzle_b32 v6, v0 offset:swizzle(SWAP,16)
	s_waitcnt lgkmcnt(0)
	v_mul_f32_e32 v5, v206, v6
	v_cndmask_b32_e64 v5, v5, -v5, vcc
	v_fmac_f32_e32 v5, v205, v0
	v_mov_b32_e32 v0, v5
	s_branch .LBB0_271
